# scan wave LDS operand loads 3 steps ahead (4 register sets), each operand waited at first use
# speedup vs baseline: 1.0013x; 1.0007x over previous
; __device__ __forceinline__ void phase_scan(const Params& p, LAS unsigned char* lds) {
;     ...
;             if (wave < 4) {
;                 if (n >= 0) {
;                     __builtin_amdgcn_s_setprio(3);
;                     const LAS float* sR = OPS + (n & 1) * SET_F + j0; const LAS float* sW = sR + 2048; const LAS float* sK = sW + 2048; const LAS float* sA = sK + 2048; const LAS float* sB = sA + 2048; const LAS float* sV = OPS + (n & 1) * SET_F + 10240;
;                     LAS float* sY = sYb + (n & 1) * 512;
;                     f32x4 a_ = *(const LAS f32x4*)(sA), w_ = *(const LAS f32x4*)(sW), b_ = *(const LAS f32x4*)(sB);
;                     f32x4 k_ = *(const LAS f32x4*)(sK), r_ = *(const LAS f32x4*)(sR);
;                     f32x4 vq[4];
; #pragma unroll
;                     for (int u = 0; u < 4; ++u) vq[u] = *(const LAS f32x4*)(sV + srow * 32 + 4 * u);
;                     f32x4 rp = r_;
; #pragma unroll
;                     for (int hb = 0; hb < 2; ++hb) {
;                         f32x4 vn[4];
; #pragma unroll
;                         for (int u = 0; u < 4; ++u) vn[u] = *(const LAS f32x4*)(sV + srow * 32 + ((16 * (hb + 1)) & 31) + 4 * u);
; #pragma unroll
;                         for (int u16 = 0; u16 < 16; ++u16) {
;                             const int s = 16 * hb + u16;
;                             const int sn = (s + 1) & 31;
;                             const f32x4 a_n = *(const LAS f32x4*)(sA + sn * 64), w_n = *(const LAS f32x4*)(sW + sn * 64), b_n = *(const LAS f32x4*)(sB + sn * 64);
;                             const f32x4 k_n = *(const LAS f32x4*)(sK + sn * 64), r_n = *(const LAS f32x4*)(sR + sn * 64);
;                             const float v = vq[u16 >> 2][u16 & 3];
;                             const f32x2 vv = {v, v};
;                             f32x2 pp = S01 * (f32x2){a_[0], a_[1]}; pp = S23 * (f32x2){a_[2], a_[3]} + pp;
;                             f32x2 yy = S01 * (f32x2){rp[0], rp[1]}; yy = S23 * (f32x2){rp[2], rp[3]} + yy;
;                             float sa = pp[0] + pp[1], y = yy[0] + yy[1];
;                             sa += dpp_f<0xB1>(sa); y += dpp_f<0xB1>(y);
;                             sa += dpp_f<0x4E>(sa); y += dpp_f<0x4E>(y);
;                             sa += dpp_f<0x141>(sa); y += dpp_f<0x141>(y);
;                             sa += dpp_f<0x140>(sa); y += dpp_f<0x140>(y);
.Lscan_wave_top:
	s_mov_b64 s[54:55], 0
	s_cmp_lt_i32 s81, 0
	s_cbranch_scc1 .LBB0_603
	s_setprio 3
	s_and_b32 s14, s81, 1
	s_mul_i32 s15, s14, 0xa800
	s_add_i32 s34, s15, 0x8800
	v_add_u32_e32 v252, s34, v178
	v_add_u32_e32 v253, s34, v179
	v_lshl_add_u32 v255, s14, 11, v184
	ds_read_b128 v[92:95], v252 offset:16384
	ds_read_b128 v[84:87], v252 offset:8192
	ds_read_b128 v[88:91], v252 offset:32768
	ds_read_b128 v[96:99], v252 offset:0
	ds_read_b128 v[80:83], v252 offset:24576
	ds_read_b128 v[236:239], v253 offset:40960
	ds_read_b128 v[112:115], v252 offset:16640
	ds_read_b128 v[104:107], v252 offset:8448
	ds_read_b128 v[108:111], v252 offset:33024
	ds_read_b128 v[116:119], v252 offset:256
	ds_read_b128 v[100:103], v252 offset:24832
	ds_read_b128 v[240:243], v253 offset:40976
	s_waitcnt lgkmcnt(7)
	v_pk_mul_f32 v[248:249], v[166:167], v[80:81]
	ds_read_b128 v[208:211], v252 offset:16896
	v_pk_fma_f32 v[248:249], v[164:165], v[82:83], v[248:249]
	ds_read_b128 v[124:127], v252 offset:8704
	v_add_f32_e32 v0, v248, v249
	s_waitcnt lgkmcnt(8)
	v_pk_mul_f32 v[202:203], v[236:237], v[92:93] op_sel_hi:[0,1]
	ds_read_b128 v[204:207], v252 offset:33280
	v_add_f32_dpp v0, v0, v0 quad_perm:[1,0,3,2] row_mask:0xf bank_mask:0xf bound_ctrl:1
	v_pk_mul_f32 v[128:129], v[236:237], v[94:95] op_sel_hi:[0,1]
	ds_read_b128 v[212:215], v252 offset:512
	v_add_f32_dpp v0, v0, v0 quad_perm:[2,3,0,1] row_mask:0xf bank_mask:0xf bound_ctrl:1
	v_pk_fma_f32 v[166:167], v[166:167], v[84:85], v[202:203]
	ds_read_b128 v[120:123], v252 offset:25088
	v_add_f32_dpp v0, v0, v0 row_half_mirror row_mask:0xf bank_mask:0xf bound_ctrl:1
	v_pk_fma_f32 v[164:165], v[164:165], v[86:87], v[128:129]
	ds_read_b128 v[228:231], v252 offset:17152
	v_add_f32_dpp v0, v0, v0 row_mirror row_mask:0xf bank_mask:0xf bound_ctrl:1
	ds_read_b128 v[220:223], v252 offset:8960
	ds_read_b128 v[224:227], v252 offset:33536
	v_pk_fma_f32 v[166:167], v[88:89], v[0:1], v[166:167] op_sel_hi:[1,0,1]
	v_pk_fma_f32 v[164:165], v[90:91], v[0:1], v[164:165] op_sel_hi:[1,0,1]
	ds_read_b128 v[232:235], v252 offset:768
	ds_read_b128 v[216:219], v252 offset:25344
	s_waitcnt lgkmcnt(11)
	v_pk_mul_f32 v[248:249], v[166:167], v[100:101]
	v_pk_mul_f32 v[250:251], v[166:167], v[96:97]
	v_pk_fma_f32 v[248:249], v[164:165], v[102:103], v[248:249]
	v_pk_fma_f32 v[250:251], v[164:165], v[98:99], v[250:251]
	v_add_f32_e32 v0, v248, v249
	v_pk_mul_f32 v[202:203], v[236:237], v[112:113] op_sel:[1,0]
	v_add_f32_e32 v78, v250, v251
	v_add_f32_dpp v0, v0, v0 quad_perm:[1,0,3,2] row_mask:0xf bank_mask:0xf bound_ctrl:1
	v_pk_mul_f32 v[128:129], v[236:237], v[114:115] op_sel:[1,0]
	v_add_f32_dpp v78, v78, v78 quad_perm:[1,0,3,2] row_mask:0xf bank_mask:0xf bound_ctrl:1
	v_add_f32_dpp v0, v0, v0 quad_perm:[2,3,0,1] row_mask:0xf bank_mask:0xf bound_ctrl:1
	v_pk_fma_f32 v[166:167], v[166:167], v[104:105], v[202:203]
	v_add_f32_dpp v78, v78, v78 quad_perm:[2,3,0,1] row_mask:0xf bank_mask:0xf bound_ctrl:1
	v_add_f32_dpp v0, v0, v0 row_half_mirror row_mask:0xf bank_mask:0xf bound_ctrl:1
	v_pk_fma_f32 v[164:165], v[164:165], v[106:107], v[128:129]
	v_add_f32_dpp v78, v78, v78 row_half_mirror row_mask:0xf bank_mask:0xf bound_ctrl:1
	v_add_f32_dpp v0, v0, v0 row_mirror row_mask:0xf bank_mask:0xf bound_ctrl:1
	ds_read_b128 v[92:95], v252 offset:17408
	v_add_f32_dpp v78, v78, v78 row_mirror row_mask:0xf bank_mask:0xf bound_ctrl:1
	v_pk_fma_f32 v[166:167], v[108:109], v[0:1], v[166:167] op_sel_hi:[1,0,1]
	v_pk_fma_f32 v[164:165], v[110:111], v[0:1], v[164:165] op_sel_hi:[1,0,1]
	ds_read_b128 v[84:87], v252 offset:9216
	ds_read_b128 v[88:91], v252 offset:33792
	ds_read_b128 v[96:99], v252 offset:1024
	ds_read_b128 v[80:83], v252 offset:25600
	ds_read_b128 v[244:247], v253 offset:40992
	s_waitcnt lgkmcnt(11)
	v_pk_mul_f32 v[248:249], v[166:167], v[120:121]
	v_pk_mul_f32 v[250:251], v[166:167], v[116:117]
	v_pk_fma_f32 v[248:249], v[164:165], v[122:123], v[248:249]
	v_pk_fma_f32 v[250:251], v[164:165], v[118:119], v[250:251]
	v_add_f32_e32 v0, v248, v249
	v_pk_mul_f32 v[202:203], v[238:239], v[208:209] op_sel_hi:[0,1]
	v_add_f32_e32 v79, v250, v251
	v_add_f32_dpp v0, v0, v0 quad_perm:[1,0,3,2] row_mask:0xf bank_mask:0xf bound_ctrl:1
	v_pk_mul_f32 v[128:129], v[238:239], v[210:211] op_sel_hi:[0,1]
	v_add_f32_dpp v79, v79, v79 quad_perm:[1,0,3,2] row_mask:0xf bank_mask:0xf bound_ctrl:1
	v_add_f32_dpp v0, v0, v0 quad_perm:[2,3,0,1] row_mask:0xf bank_mask:0xf bound_ctrl:1
	v_pk_fma_f32 v[166:167], v[166:167], v[124:125], v[202:203]
	v_add_f32_dpp v79, v79, v79 quad_perm:[2,3,0,1] row_mask:0xf bank_mask:0xf bound_ctrl:1
	v_add_f32_dpp v0, v0, v0 row_half_mirror row_mask:0xf bank_mask:0xf bound_ctrl:1
	v_pk_fma_f32 v[164:165], v[164:165], v[126:127], v[128:129]
	v_add_f32_dpp v79, v79, v79 row_half_mirror row_mask:0xf bank_mask:0xf bound_ctrl:1
	v_add_f32_dpp v0, v0, v0 row_mirror row_mask:0xf bank_mask:0xf bound_ctrl:1
	ds_read_b128 v[112:115], v252 offset:17664
	v_add_f32_dpp v79, v79, v79 row_mirror row_mask:0xf bank_mask:0xf bound_ctrl:1
	v_pk_fma_f32 v[166:167], v[204:205], v[0:1], v[166:167] op_sel_hi:[1,0,1]
	v_pk_fma_f32 v[164:165], v[206:207], v[0:1], v[164:165] op_sel_hi:[1,0,1]
	ds_write2_b32 v255, v78, v79 offset1:16
	ds_read_b128 v[104:107], v252 offset:9472
	ds_read_b128 v[108:111], v252 offset:34048
	ds_read_b128 v[116:119], v252 offset:1280
	ds_read_b128 v[100:103], v252 offset:25856
	s_waitcnt lgkmcnt(12)
; #define LAS __attribute__((address_space(3)))
; template <int CTRL> __device__ __forceinline__ float dpp_f(float x) { return __int_as_float(__builtin_amdgcn_update_dpp(0, __float_as_int(x), CTRL, 0xf, 0xf, false)); }
; __device__ __forceinline__ void phase_scan(const Params& p, LAS unsigned char* lds) {
;     ...
;                         for (int u16 = 0; u16 < 16; ++u16) {
;                             const int s = 16 * hb + u16;
;                             const int sn = (s + 1) & 31;
;                             const f32x4 a_n = *(const LAS f32x4*)(sA + sn * 64), w_n = *(const LAS f32x4*)(sW + sn * 64), b_n = *(const LAS f32x4*)(sB + sn * 64);
;                             const f32x4 k_n = *(const LAS f32x4*)(sK + sn * 64), r_n = *(const LAS f32x4*)(sR + sn * 64);
;                             const float v = vq[u16 >> 2][u16 & 3];
;                             const f32x2 vv = {v, v};
;                             f32x2 pp = S01 * (f32x2){a_[0], a_[1]}; pp = S23 * (f32x2){a_[2], a_[3]} + pp;
;                             f32x2 yy = S01 * (f32x2){rp[0], rp[1]}; yy = S23 * (f32x2){rp[2], rp[3]} + yy;
;                             float sa = pp[0] + pp[1], y = yy[0] + yy[1];
;                             sa += dpp_f<0xB1>(sa); y += dpp_f<0xB1>(y);
;                             sa += dpp_f<0x4E>(sa); y += dpp_f<0x4E>(y);
;                             sa += dpp_f<0x141>(sa); y += dpp_f<0x141>(y);
;                             sa += dpp_f<0x140>(sa); y += dpp_f<0x140>(y);
;                             sY[((s - 1) & 31) * 16 + srow] = y;
;                             const f32x2 sv = {sa, sa};
;                             S01 = S01 * (f32x2){w_[0], w_[1]} + vv * (f32x2){k_[0], k_[1]};
;                             S23 = S23 * (f32x2){w_[2], w_[3]} + vv * (f32x2){k_[2], k_[3]};
;                             S01 = sv * (f32x2){b_[0], b_[1]} + S01;
;                             S23 = sv * (f32x2){b_[2], b_[3]} + S23;
;                             rp = r_;
;                             a_ = a_n; w_ = w_n; b_ = b_n; k_ = k_n; r_ = r_n;
;                         }
	v_pk_mul_f32 v[248:249], v[166:167], v[216:217]
	v_pk_mul_f32 v[250:251], v[166:167], v[212:213]
	v_pk_fma_f32 v[248:249], v[164:165], v[218:219], v[248:249]
	v_pk_fma_f32 v[250:251], v[164:165], v[214:215], v[250:251]
	v_add_f32_e32 v0, v248, v249
	v_pk_mul_f32 v[202:203], v[238:239], v[228:229] op_sel:[1,0]
	v_add_f32_e32 v78, v250, v251
	v_add_f32_dpp v0, v0, v0 quad_perm:[1,0,3,2] row_mask:0xf bank_mask:0xf bound_ctrl:1
	v_pk_mul_f32 v[128:129], v[238:239], v[230:231] op_sel:[1,0]
	v_add_f32_dpp v78, v78, v78 quad_perm:[1,0,3,2] row_mask:0xf bank_mask:0xf bound_ctrl:1
	v_add_f32_dpp v0, v0, v0 quad_perm:[2,3,0,1] row_mask:0xf bank_mask:0xf bound_ctrl:1
	v_pk_fma_f32 v[166:167], v[166:167], v[220:221], v[202:203]
	v_add_f32_dpp v78, v78, v78 quad_perm:[2,3,0,1] row_mask:0xf bank_mask:0xf bound_ctrl:1
	v_add_f32_dpp v0, v0, v0 row_half_mirror row_mask:0xf bank_mask:0xf bound_ctrl:1
	v_pk_fma_f32 v[164:165], v[164:165], v[222:223], v[128:129]
	v_add_f32_dpp v78, v78, v78 row_half_mirror row_mask:0xf bank_mask:0xf bound_ctrl:1
	v_add_f32_dpp v0, v0, v0 row_mirror row_mask:0xf bank_mask:0xf bound_ctrl:1
	ds_read_b128 v[208:211], v252 offset:17920
	v_add_f32_dpp v78, v78, v78 row_mirror row_mask:0xf bank_mask:0xf bound_ctrl:1
	v_pk_fma_f32 v[166:167], v[224:225], v[0:1], v[166:167] op_sel_hi:[1,0,1]
	v_pk_fma_f32 v[164:165], v[226:227], v[0:1], v[164:165] op_sel_hi:[1,0,1]
	ds_read_b128 v[124:127], v252 offset:9728
	ds_read_b128 v[204:207], v252 offset:34304
	ds_read_b128 v[212:215], v252 offset:1536
	ds_read_b128 v[120:123], v252 offset:26112
	s_waitcnt lgkmcnt(12)
	v_pk_mul_f32 v[248:249], v[166:167], v[80:81]
	v_pk_mul_f32 v[250:251], v[166:167], v[232:233]
	v_pk_fma_f32 v[248:249], v[164:165], v[82:83], v[248:249]
	v_pk_fma_f32 v[250:251], v[164:165], v[234:235], v[250:251]
	v_add_f32_e32 v0, v248, v249
	v_pk_mul_f32 v[202:203], v[240:241], v[92:93] op_sel_hi:[0,1]
	v_add_f32_e32 v79, v250, v251
	v_add_f32_dpp v0, v0, v0 quad_perm:[1,0,3,2] row_mask:0xf bank_mask:0xf bound_ctrl:1
	v_pk_mul_f32 v[128:129], v[240:241], v[94:95] op_sel_hi:[0,1]
	v_add_f32_dpp v79, v79, v79 quad_perm:[1,0,3,2] row_mask:0xf bank_mask:0xf bound_ctrl:1
	v_add_f32_dpp v0, v0, v0 quad_perm:[2,3,0,1] row_mask:0xf bank_mask:0xf bound_ctrl:1
	v_pk_fma_f32 v[166:167], v[166:167], v[84:85], v[202:203]
	v_add_f32_dpp v79, v79, v79 quad_perm:[2,3,0,1] row_mask:0xf bank_mask:0xf bound_ctrl:1
	v_add_f32_dpp v0, v0, v0 row_half_mirror row_mask:0xf bank_mask:0xf bound_ctrl:1
	v_pk_fma_f32 v[164:165], v[164:165], v[86:87], v[128:129]
	v_add_f32_dpp v79, v79, v79 row_half_mirror row_mask:0xf bank_mask:0xf bound_ctrl:1
	v_add_f32_dpp v0, v0, v0 row_mirror row_mask:0xf bank_mask:0xf bound_ctrl:1
	ds_read_b128 v[228:231], v252 offset:18176
	v_add_f32_dpp v79, v79, v79 row_mirror row_mask:0xf bank_mask:0xf bound_ctrl:1
	v_pk_fma_f32 v[166:167], v[88:89], v[0:1], v[166:167] op_sel_hi:[1,0,1]
	v_pk_fma_f32 v[164:165], v[90:91], v[0:1], v[164:165] op_sel_hi:[1,0,1]
	ds_write2_b32 v255, v78, v79 offset0:32 offset1:48
	ds_read_b128 v[220:223], v252 offset:9984
	ds_read_b128 v[224:227], v252 offset:34560
	ds_read_b128 v[232:235], v252 offset:1792
	ds_read_b128 v[216:219], v252 offset:26368
	s_waitcnt lgkmcnt(11)
	v_pk_mul_f32 v[248:249], v[166:167], v[100:101]
	v_pk_mul_f32 v[250:251], v[166:167], v[96:97]
	v_pk_fma_f32 v[248:249], v[164:165], v[102:103], v[248:249]
	v_pk_fma_f32 v[250:251], v[164:165], v[98:99], v[250:251]
	v_add_f32_e32 v0, v248, v249
	v_pk_mul_f32 v[202:203], v[240:241], v[112:113] op_sel:[1,0]
	v_add_f32_e32 v78, v250, v251
	v_add_f32_dpp v0, v0, v0 quad_perm:[1,0,3,2] row_mask:0xf bank_mask:0xf bound_ctrl:1
	v_pk_mul_f32 v[128:129], v[240:241], v[114:115] op_sel:[1,0]
	v_add_f32_dpp v78, v78, v78 quad_perm:[1,0,3,2] row_mask:0xf bank_mask:0xf bound_ctrl:1
	v_add_f32_dpp v0, v0, v0 quad_perm:[2,3,0,1] row_mask:0xf bank_mask:0xf bound_ctrl:1
	v_pk_fma_f32 v[166:167], v[166:167], v[104:105], v[202:203]
	v_add_f32_dpp v78, v78, v78 quad_perm:[2,3,0,1] row_mask:0xf bank_mask:0xf bound_ctrl:1
	v_add_f32_dpp v0, v0, v0 row_half_mirror row_mask:0xf bank_mask:0xf bound_ctrl:1
	v_pk_fma_f32 v[164:165], v[164:165], v[106:107], v[128:129]
	v_add_f32_dpp v78, v78, v78 row_half_mirror row_mask:0xf bank_mask:0xf bound_ctrl:1
	v_add_f32_dpp v0, v0, v0 row_mirror row_mask:0xf bank_mask:0xf bound_ctrl:1
	ds_read_b128 v[92:95], v252 offset:18432
	v_add_f32_dpp v78, v78, v78 row_mirror row_mask:0xf bank_mask:0xf bound_ctrl:1
	v_pk_fma_f32 v[166:167], v[108:109], v[0:1], v[166:167] op_sel_hi:[1,0,1]
	v_pk_fma_f32 v[164:165], v[110:111], v[0:1], v[164:165] op_sel_hi:[1,0,1]
	ds_read_b128 v[84:87], v252 offset:10240
	ds_read_b128 v[88:91], v252 offset:34816
	ds_read_b128 v[96:99], v252 offset:2048
	ds_read_b128 v[80:83], v252 offset:26624
	ds_read_b128 v[236:239], v253 offset:41008
	s_waitcnt lgkmcnt(12)
; #define LAS __attribute__((address_space(3)))
; template <int CTRL> __device__ __forceinline__ float dpp_f(float x) { return __int_as_float(__builtin_amdgcn_update_dpp(0, __float_as_int(x), CTRL, 0xf, 0xf, false)); }
; __device__ __forceinline__ void phase_scan(const Params& p, LAS unsigned char* lds) {
;     ...
;                         for (int u16 = 0; u16 < 16; ++u16) {
;                             const int s = 16 * hb + u16;
;                             const int sn = (s + 1) & 31;
;                             const f32x4 a_n = *(const LAS f32x4*)(sA + sn * 64), w_n = *(const LAS f32x4*)(sW + sn * 64), b_n = *(const LAS f32x4*)(sB + sn * 64);
;                             const f32x4 k_n = *(const LAS f32x4*)(sK + sn * 64), r_n = *(const LAS f32x4*)(sR + sn * 64);
;                             const float v = vq[u16 >> 2][u16 & 3];
;                             const f32x2 vv = {v, v};
;                             f32x2 pp = S01 * (f32x2){a_[0], a_[1]}; pp = S23 * (f32x2){a_[2], a_[3]} + pp;
;                             f32x2 yy = S01 * (f32x2){rp[0], rp[1]}; yy = S23 * (f32x2){rp[2], rp[3]} + yy;
;                             float sa = pp[0] + pp[1], y = yy[0] + yy[1];
;                             sa += dpp_f<0xB1>(sa); y += dpp_f<0xB1>(y);
;                             sa += dpp_f<0x4E>(sa); y += dpp_f<0x4E>(y);
;                             sa += dpp_f<0x141>(sa); y += dpp_f<0x141>(y);
;                             sa += dpp_f<0x140>(sa); y += dpp_f<0x140>(y);
;                             sY[((s - 1) & 31) * 16 + srow] = y;
;                             const f32x2 sv = {sa, sa};
;                             S01 = S01 * (f32x2){w_[0], w_[1]} + vv * (f32x2){k_[0], k_[1]};
;                             S23 = S23 * (f32x2){w_[2], w_[3]} + vv * (f32x2){k_[2], k_[3]};
;                             S01 = sv * (f32x2){b_[0], b_[1]} + S01;
;                             S23 = sv * (f32x2){b_[2], b_[3]} + S23;
;                             rp = r_;
;                             a_ = a_n; w_ = w_n; b_ = b_n; k_ = k_n; r_ = r_n;
;                         }
	v_pk_mul_f32 v[248:249], v[166:167], v[120:121]
	v_pk_mul_f32 v[250:251], v[166:167], v[116:117]
	v_pk_fma_f32 v[248:249], v[164:165], v[122:123], v[248:249]
	v_pk_fma_f32 v[250:251], v[164:165], v[118:119], v[250:251]
	v_add_f32_e32 v0, v248, v249
	v_pk_mul_f32 v[202:203], v[242:243], v[208:209] op_sel_hi:[0,1]
	v_add_f32_e32 v79, v250, v251
	v_add_f32_dpp v0, v0, v0 quad_perm:[1,0,3,2] row_mask:0xf bank_mask:0xf bound_ctrl:1
	v_pk_mul_f32 v[128:129], v[242:243], v[210:211] op_sel_hi:[0,1]
	v_add_f32_dpp v79, v79, v79 quad_perm:[1,0,3,2] row_mask:0xf bank_mask:0xf bound_ctrl:1
	v_add_f32_dpp v0, v0, v0 quad_perm:[2,3,0,1] row_mask:0xf bank_mask:0xf bound_ctrl:1
	v_pk_fma_f32 v[166:167], v[166:167], v[124:125], v[202:203]
	v_add_f32_dpp v79, v79, v79 quad_perm:[2,3,0,1] row_mask:0xf bank_mask:0xf bound_ctrl:1
	v_add_f32_dpp v0, v0, v0 row_half_mirror row_mask:0xf bank_mask:0xf bound_ctrl:1
	v_pk_fma_f32 v[164:165], v[164:165], v[126:127], v[128:129]
	v_add_f32_dpp v79, v79, v79 row_half_mirror row_mask:0xf bank_mask:0xf bound_ctrl:1
	v_add_f32_dpp v0, v0, v0 row_mirror row_mask:0xf bank_mask:0xf bound_ctrl:1
	ds_read_b128 v[112:115], v252 offset:18688
	v_add_f32_dpp v79, v79, v79 row_mirror row_mask:0xf bank_mask:0xf bound_ctrl:1
	v_pk_fma_f32 v[166:167], v[204:205], v[0:1], v[166:167] op_sel_hi:[1,0,1]
	v_pk_fma_f32 v[164:165], v[206:207], v[0:1], v[164:165] op_sel_hi:[1,0,1]
	ds_write2_b32 v255, v78, v79 offset0:64 offset1:80
	ds_read_b128 v[104:107], v252 offset:10496
	ds_read_b128 v[108:111], v252 offset:35072
	ds_read_b128 v[116:119], v252 offset:2304
	ds_read_b128 v[100:103], v252 offset:26880
	s_waitcnt lgkmcnt(12)
	v_pk_mul_f32 v[248:249], v[166:167], v[216:217]
	v_pk_mul_f32 v[250:251], v[166:167], v[212:213]
	v_pk_fma_f32 v[248:249], v[164:165], v[218:219], v[248:249]
	v_pk_fma_f32 v[250:251], v[164:165], v[214:215], v[250:251]
	v_add_f32_e32 v0, v248, v249
	v_pk_mul_f32 v[202:203], v[242:243], v[228:229] op_sel:[1,0]
	v_add_f32_e32 v78, v250, v251
	v_add_f32_dpp v0, v0, v0 quad_perm:[1,0,3,2] row_mask:0xf bank_mask:0xf bound_ctrl:1
	v_pk_mul_f32 v[128:129], v[242:243], v[230:231] op_sel:[1,0]
	v_add_f32_dpp v78, v78, v78 quad_perm:[1,0,3,2] row_mask:0xf bank_mask:0xf bound_ctrl:1
	v_add_f32_dpp v0, v0, v0 quad_perm:[2,3,0,1] row_mask:0xf bank_mask:0xf bound_ctrl:1
	v_pk_fma_f32 v[166:167], v[166:167], v[220:221], v[202:203]
	v_add_f32_dpp v78, v78, v78 quad_perm:[2,3,0,1] row_mask:0xf bank_mask:0xf bound_ctrl:1
	v_add_f32_dpp v0, v0, v0 row_half_mirror row_mask:0xf bank_mask:0xf bound_ctrl:1
	v_pk_fma_f32 v[164:165], v[164:165], v[222:223], v[128:129]
	v_add_f32_dpp v78, v78, v78 row_half_mirror row_mask:0xf bank_mask:0xf bound_ctrl:1
	v_add_f32_dpp v0, v0, v0 row_mirror row_mask:0xf bank_mask:0xf bound_ctrl:1
	ds_read_b128 v[208:211], v252 offset:18944
	v_add_f32_dpp v78, v78, v78 row_mirror row_mask:0xf bank_mask:0xf bound_ctrl:1
	v_pk_fma_f32 v[166:167], v[224:225], v[0:1], v[166:167] op_sel_hi:[1,0,1]
	v_pk_fma_f32 v[164:165], v[226:227], v[0:1], v[164:165] op_sel_hi:[1,0,1]
	ds_read_b128 v[124:127], v252 offset:10752
	ds_read_b128 v[204:207], v252 offset:35328
	ds_read_b128 v[212:215], v252 offset:2560
	ds_read_b128 v[120:123], v252 offset:27136
	s_waitcnt lgkmcnt(12)
	v_pk_mul_f32 v[248:249], v[166:167], v[80:81]
	v_pk_mul_f32 v[250:251], v[166:167], v[232:233]
	v_pk_fma_f32 v[248:249], v[164:165], v[82:83], v[248:249]
	v_pk_fma_f32 v[250:251], v[164:165], v[234:235], v[250:251]
	v_add_f32_e32 v0, v248, v249
	v_pk_mul_f32 v[202:203], v[244:245], v[92:93] op_sel_hi:[0,1]
	v_add_f32_e32 v79, v250, v251
	v_add_f32_dpp v0, v0, v0 quad_perm:[1,0,3,2] row_mask:0xf bank_mask:0xf bound_ctrl:1
	v_pk_mul_f32 v[128:129], v[244:245], v[94:95] op_sel_hi:[0,1]
	v_add_f32_dpp v79, v79, v79 quad_perm:[1,0,3,2] row_mask:0xf bank_mask:0xf bound_ctrl:1
	v_add_f32_dpp v0, v0, v0 quad_perm:[2,3,0,1] row_mask:0xf bank_mask:0xf bound_ctrl:1
	v_pk_fma_f32 v[166:167], v[166:167], v[84:85], v[202:203]
	v_add_f32_dpp v79, v79, v79 quad_perm:[2,3,0,1] row_mask:0xf bank_mask:0xf bound_ctrl:1
	v_add_f32_dpp v0, v0, v0 row_half_mirror row_mask:0xf bank_mask:0xf bound_ctrl:1
	v_pk_fma_f32 v[164:165], v[164:165], v[86:87], v[128:129]
	v_add_f32_dpp v79, v79, v79 row_half_mirror row_mask:0xf bank_mask:0xf bound_ctrl:1
	v_add_f32_dpp v0, v0, v0 row_mirror row_mask:0xf bank_mask:0xf bound_ctrl:1
	ds_read_b128 v[228:231], v252 offset:19200
	v_add_f32_dpp v79, v79, v79 row_mirror row_mask:0xf bank_mask:0xf bound_ctrl:1
	v_pk_fma_f32 v[166:167], v[88:89], v[0:1], v[166:167] op_sel_hi:[1,0,1]
	v_pk_fma_f32 v[164:165], v[90:91], v[0:1], v[164:165] op_sel_hi:[1,0,1]
	ds_write2_b32 v255, v78, v79 offset0:96 offset1:112
	ds_read_b128 v[220:223], v252 offset:11008
	ds_read_b128 v[224:227], v252 offset:35584
	ds_read_b128 v[232:235], v252 offset:2816
	ds_read_b128 v[216:219], v252 offset:27392
	s_waitcnt lgkmcnt(11)
; #define LAS __attribute__((address_space(3)))
; template <int CTRL> __device__ __forceinline__ float dpp_f(float x) { return __int_as_float(__builtin_amdgcn_update_dpp(0, __float_as_int(x), CTRL, 0xf, 0xf, false)); }
; __device__ __forceinline__ void phase_scan(const Params& p, LAS unsigned char* lds) {
;     ...
;                         for (int u16 = 0; u16 < 16; ++u16) {
;                             const int s = 16 * hb + u16;
;                             const int sn = (s + 1) & 31;
;                             const f32x4 a_n = *(const LAS f32x4*)(sA + sn * 64), w_n = *(const LAS f32x4*)(sW + sn * 64), b_n = *(const LAS f32x4*)(sB + sn * 64);
;                             const f32x4 k_n = *(const LAS f32x4*)(sK + sn * 64), r_n = *(const LAS f32x4*)(sR + sn * 64);
;                             const float v = vq[u16 >> 2][u16 & 3];
;                             const f32x2 vv = {v, v};
;                             f32x2 pp = S01 * (f32x2){a_[0], a_[1]}; pp = S23 * (f32x2){a_[2], a_[3]} + pp;
;                             f32x2 yy = S01 * (f32x2){rp[0], rp[1]}; yy = S23 * (f32x2){rp[2], rp[3]} + yy;
;                             float sa = pp[0] + pp[1], y = yy[0] + yy[1];
;                             sa += dpp_f<0xB1>(sa); y += dpp_f<0xB1>(y);
;                             sa += dpp_f<0x4E>(sa); y += dpp_f<0x4E>(y);
;                             sa += dpp_f<0x141>(sa); y += dpp_f<0x141>(y);
;                             sa += dpp_f<0x140>(sa); y += dpp_f<0x140>(y);
;                             sY[((s - 1) & 31) * 16 + srow] = y;
;                             const f32x2 sv = {sa, sa};
;                             S01 = S01 * (f32x2){w_[0], w_[1]} + vv * (f32x2){k_[0], k_[1]};
;                             S23 = S23 * (f32x2){w_[2], w_[3]} + vv * (f32x2){k_[2], k_[3]};
;                             S01 = sv * (f32x2){b_[0], b_[1]} + S01;
;                             S23 = sv * (f32x2){b_[2], b_[3]} + S23;
;                             rp = r_;
;                             a_ = a_n; w_ = w_n; b_ = b_n; k_ = k_n; r_ = r_n;
;                         }
	v_pk_mul_f32 v[248:249], v[166:167], v[100:101]
	v_pk_mul_f32 v[250:251], v[166:167], v[96:97]
	v_pk_fma_f32 v[248:249], v[164:165], v[102:103], v[248:249]
	v_pk_fma_f32 v[250:251], v[164:165], v[98:99], v[250:251]
	v_add_f32_e32 v0, v248, v249
	v_pk_mul_f32 v[202:203], v[244:245], v[112:113] op_sel:[1,0]
	v_add_f32_e32 v78, v250, v251
	v_add_f32_dpp v0, v0, v0 quad_perm:[1,0,3,2] row_mask:0xf bank_mask:0xf bound_ctrl:1
	v_pk_mul_f32 v[128:129], v[244:245], v[114:115] op_sel:[1,0]
	v_add_f32_dpp v78, v78, v78 quad_perm:[1,0,3,2] row_mask:0xf bank_mask:0xf bound_ctrl:1
	v_add_f32_dpp v0, v0, v0 quad_perm:[2,3,0,1] row_mask:0xf bank_mask:0xf bound_ctrl:1
	v_pk_fma_f32 v[166:167], v[166:167], v[104:105], v[202:203]
	v_add_f32_dpp v78, v78, v78 quad_perm:[2,3,0,1] row_mask:0xf bank_mask:0xf bound_ctrl:1
	v_add_f32_dpp v0, v0, v0 row_half_mirror row_mask:0xf bank_mask:0xf bound_ctrl:1
	v_pk_fma_f32 v[164:165], v[164:165], v[106:107], v[128:129]
	v_add_f32_dpp v78, v78, v78 row_half_mirror row_mask:0xf bank_mask:0xf bound_ctrl:1
	v_add_f32_dpp v0, v0, v0 row_mirror row_mask:0xf bank_mask:0xf bound_ctrl:1
	ds_read_b128 v[92:95], v252 offset:19456
	v_add_f32_dpp v78, v78, v78 row_mirror row_mask:0xf bank_mask:0xf bound_ctrl:1
	v_pk_fma_f32 v[166:167], v[108:109], v[0:1], v[166:167] op_sel_hi:[1,0,1]
	v_pk_fma_f32 v[164:165], v[110:111], v[0:1], v[164:165] op_sel_hi:[1,0,1]
	ds_read_b128 v[84:87], v252 offset:11264
	ds_read_b128 v[88:91], v252 offset:35840
	ds_read_b128 v[96:99], v252 offset:3072
	ds_read_b128 v[80:83], v252 offset:27648
	ds_read_b128 v[240:243], v253 offset:41024
	s_waitcnt lgkmcnt(12)
	v_pk_mul_f32 v[248:249], v[166:167], v[120:121]
	v_pk_mul_f32 v[250:251], v[166:167], v[116:117]
	v_pk_fma_f32 v[248:249], v[164:165], v[122:123], v[248:249]
	v_pk_fma_f32 v[250:251], v[164:165], v[118:119], v[250:251]
	v_add_f32_e32 v0, v248, v249
	v_pk_mul_f32 v[202:203], v[246:247], v[208:209] op_sel_hi:[0,1]
	v_add_f32_e32 v79, v250, v251
	v_add_f32_dpp v0, v0, v0 quad_perm:[1,0,3,2] row_mask:0xf bank_mask:0xf bound_ctrl:1
	v_pk_mul_f32 v[128:129], v[246:247], v[210:211] op_sel_hi:[0,1]
	v_add_f32_dpp v79, v79, v79 quad_perm:[1,0,3,2] row_mask:0xf bank_mask:0xf bound_ctrl:1
	v_add_f32_dpp v0, v0, v0 quad_perm:[2,3,0,1] row_mask:0xf bank_mask:0xf bound_ctrl:1
	v_pk_fma_f32 v[166:167], v[166:167], v[124:125], v[202:203]
	v_add_f32_dpp v79, v79, v79 quad_perm:[2,3,0,1] row_mask:0xf bank_mask:0xf bound_ctrl:1
	v_add_f32_dpp v0, v0, v0 row_half_mirror row_mask:0xf bank_mask:0xf bound_ctrl:1
	v_pk_fma_f32 v[164:165], v[164:165], v[126:127], v[128:129]
	v_add_f32_dpp v79, v79, v79 row_half_mirror row_mask:0xf bank_mask:0xf bound_ctrl:1
	v_add_f32_dpp v0, v0, v0 row_mirror row_mask:0xf bank_mask:0xf bound_ctrl:1
	ds_read_b128 v[112:115], v252 offset:19712
	v_add_f32_dpp v79, v79, v79 row_mirror row_mask:0xf bank_mask:0xf bound_ctrl:1
	v_pk_fma_f32 v[166:167], v[204:205], v[0:1], v[166:167] op_sel_hi:[1,0,1]
	v_pk_fma_f32 v[164:165], v[206:207], v[0:1], v[164:165] op_sel_hi:[1,0,1]
	ds_write2_b32 v255, v78, v79 offset0:128 offset1:144
	ds_read_b128 v[104:107], v252 offset:11520
	ds_read_b128 v[108:111], v252 offset:36096
	ds_read_b128 v[116:119], v252 offset:3328
	ds_read_b128 v[100:103], v252 offset:27904
	s_waitcnt lgkmcnt(12)
	v_pk_mul_f32 v[248:249], v[166:167], v[216:217]
	v_pk_mul_f32 v[250:251], v[166:167], v[212:213]
	v_pk_fma_f32 v[248:249], v[164:165], v[218:219], v[248:249]
	v_pk_fma_f32 v[250:251], v[164:165], v[214:215], v[250:251]
	v_add_f32_e32 v0, v248, v249
	v_pk_mul_f32 v[202:203], v[246:247], v[228:229] op_sel:[1,0]
	v_add_f32_e32 v78, v250, v251
	v_add_f32_dpp v0, v0, v0 quad_perm:[1,0,3,2] row_mask:0xf bank_mask:0xf bound_ctrl:1
	v_pk_mul_f32 v[128:129], v[246:247], v[230:231] op_sel:[1,0]
	v_add_f32_dpp v78, v78, v78 quad_perm:[1,0,3,2] row_mask:0xf bank_mask:0xf bound_ctrl:1
	v_add_f32_dpp v0, v0, v0 quad_perm:[2,3,0,1] row_mask:0xf bank_mask:0xf bound_ctrl:1
	v_pk_fma_f32 v[166:167], v[166:167], v[220:221], v[202:203]
	v_add_f32_dpp v78, v78, v78 quad_perm:[2,3,0,1] row_mask:0xf bank_mask:0xf bound_ctrl:1
	v_add_f32_dpp v0, v0, v0 row_half_mirror row_mask:0xf bank_mask:0xf bound_ctrl:1
	v_pk_fma_f32 v[164:165], v[164:165], v[222:223], v[128:129]
	v_add_f32_dpp v78, v78, v78 row_half_mirror row_mask:0xf bank_mask:0xf bound_ctrl:1
	v_add_f32_dpp v0, v0, v0 row_mirror row_mask:0xf bank_mask:0xf bound_ctrl:1
	ds_read_b128 v[208:211], v252 offset:19968
	v_add_f32_dpp v78, v78, v78 row_mirror row_mask:0xf bank_mask:0xf bound_ctrl:1
	v_pk_fma_f32 v[166:167], v[224:225], v[0:1], v[166:167] op_sel_hi:[1,0,1]
	v_pk_fma_f32 v[164:165], v[226:227], v[0:1], v[164:165] op_sel_hi:[1,0,1]
	ds_read_b128 v[124:127], v252 offset:11776
	ds_read_b128 v[204:207], v252 offset:36352
	ds_read_b128 v[212:215], v252 offset:3584
	ds_read_b128 v[120:123], v252 offset:28160
	s_waitcnt lgkmcnt(12)
; #define LAS __attribute__((address_space(3)))
; template <int CTRL> __device__ __forceinline__ float dpp_f(float x) { return __int_as_float(__builtin_amdgcn_update_dpp(0, __float_as_int(x), CTRL, 0xf, 0xf, false)); }
; __device__ __forceinline__ void phase_scan(const Params& p, LAS unsigned char* lds) {
;     ...
;                         for (int u16 = 0; u16 < 16; ++u16) {
;                             const int s = 16 * hb + u16;
;                             const int sn = (s + 1) & 31;
;                             const f32x4 a_n = *(const LAS f32x4*)(sA + sn * 64), w_n = *(const LAS f32x4*)(sW + sn * 64), b_n = *(const LAS f32x4*)(sB + sn * 64);
;                             const f32x4 k_n = *(const LAS f32x4*)(sK + sn * 64), r_n = *(const LAS f32x4*)(sR + sn * 64);
;                             const float v = vq[u16 >> 2][u16 & 3];
;                             const f32x2 vv = {v, v};
;                             f32x2 pp = S01 * (f32x2){a_[0], a_[1]}; pp = S23 * (f32x2){a_[2], a_[3]} + pp;
;                             f32x2 yy = S01 * (f32x2){rp[0], rp[1]}; yy = S23 * (f32x2){rp[2], rp[3]} + yy;
;                             float sa = pp[0] + pp[1], y = yy[0] + yy[1];
;                             sa += dpp_f<0xB1>(sa); y += dpp_f<0xB1>(y);
;                             sa += dpp_f<0x4E>(sa); y += dpp_f<0x4E>(y);
;                             sa += dpp_f<0x141>(sa); y += dpp_f<0x141>(y);
;                             sa += dpp_f<0x140>(sa); y += dpp_f<0x140>(y);
;                             sY[((s - 1) & 31) * 16 + srow] = y;
;                             const f32x2 sv = {sa, sa};
;                             S01 = S01 * (f32x2){w_[0], w_[1]} + vv * (f32x2){k_[0], k_[1]};
;                             S23 = S23 * (f32x2){w_[2], w_[3]} + vv * (f32x2){k_[2], k_[3]};
;                             S01 = sv * (f32x2){b_[0], b_[1]} + S01;
;                             S23 = sv * (f32x2){b_[2], b_[3]} + S23;
;                             rp = r_;
;                             a_ = a_n; w_ = w_n; b_ = b_n; k_ = k_n; r_ = r_n;
;                         }
	v_pk_mul_f32 v[248:249], v[166:167], v[80:81]
	v_pk_mul_f32 v[250:251], v[166:167], v[232:233]
	v_pk_fma_f32 v[248:249], v[164:165], v[82:83], v[248:249]
	v_pk_fma_f32 v[250:251], v[164:165], v[234:235], v[250:251]
	v_add_f32_e32 v0, v248, v249
	v_pk_mul_f32 v[202:203], v[236:237], v[92:93] op_sel_hi:[0,1]
	v_add_f32_e32 v79, v250, v251
	v_add_f32_dpp v0, v0, v0 quad_perm:[1,0,3,2] row_mask:0xf bank_mask:0xf bound_ctrl:1
	v_pk_mul_f32 v[128:129], v[236:237], v[94:95] op_sel_hi:[0,1]
	v_add_f32_dpp v79, v79, v79 quad_perm:[1,0,3,2] row_mask:0xf bank_mask:0xf bound_ctrl:1
	v_add_f32_dpp v0, v0, v0 quad_perm:[2,3,0,1] row_mask:0xf bank_mask:0xf bound_ctrl:1
	v_pk_fma_f32 v[166:167], v[166:167], v[84:85], v[202:203]
	v_add_f32_dpp v79, v79, v79 quad_perm:[2,3,0,1] row_mask:0xf bank_mask:0xf bound_ctrl:1
	v_add_f32_dpp v0, v0, v0 row_half_mirror row_mask:0xf bank_mask:0xf bound_ctrl:1
	v_pk_fma_f32 v[164:165], v[164:165], v[86:87], v[128:129]
	v_add_f32_dpp v79, v79, v79 row_half_mirror row_mask:0xf bank_mask:0xf bound_ctrl:1
	v_add_f32_dpp v0, v0, v0 row_mirror row_mask:0xf bank_mask:0xf bound_ctrl:1
	ds_read_b128 v[228:231], v252 offset:20224
	v_add_f32_dpp v79, v79, v79 row_mirror row_mask:0xf bank_mask:0xf bound_ctrl:1
	v_pk_fma_f32 v[166:167], v[88:89], v[0:1], v[166:167] op_sel_hi:[1,0,1]
	v_pk_fma_f32 v[164:165], v[90:91], v[0:1], v[164:165] op_sel_hi:[1,0,1]
	ds_write2_b32 v255, v78, v79 offset0:160 offset1:176
	ds_read_b128 v[220:223], v252 offset:12032
	ds_read_b128 v[224:227], v252 offset:36608
	ds_read_b128 v[232:235], v252 offset:3840
	ds_read_b128 v[216:219], v252 offset:28416
	s_waitcnt lgkmcnt(11)
	v_pk_mul_f32 v[248:249], v[166:167], v[100:101]
	v_pk_mul_f32 v[250:251], v[166:167], v[96:97]
	v_pk_fma_f32 v[248:249], v[164:165], v[102:103], v[248:249]
	v_pk_fma_f32 v[250:251], v[164:165], v[98:99], v[250:251]
	v_add_f32_e32 v0, v248, v249
	v_pk_mul_f32 v[202:203], v[236:237], v[112:113] op_sel:[1,0]
	v_add_f32_e32 v78, v250, v251
	v_add_f32_dpp v0, v0, v0 quad_perm:[1,0,3,2] row_mask:0xf bank_mask:0xf bound_ctrl:1
	v_pk_mul_f32 v[128:129], v[236:237], v[114:115] op_sel:[1,0]
	v_add_f32_dpp v78, v78, v78 quad_perm:[1,0,3,2] row_mask:0xf bank_mask:0xf bound_ctrl:1
	v_add_f32_dpp v0, v0, v0 quad_perm:[2,3,0,1] row_mask:0xf bank_mask:0xf bound_ctrl:1
	v_pk_fma_f32 v[166:167], v[166:167], v[104:105], v[202:203]
	v_add_f32_dpp v78, v78, v78 quad_perm:[2,3,0,1] row_mask:0xf bank_mask:0xf bound_ctrl:1
	v_add_f32_dpp v0, v0, v0 row_half_mirror row_mask:0xf bank_mask:0xf bound_ctrl:1
	v_pk_fma_f32 v[164:165], v[164:165], v[106:107], v[128:129]
	v_add_f32_dpp v78, v78, v78 row_half_mirror row_mask:0xf bank_mask:0xf bound_ctrl:1
	v_add_f32_dpp v0, v0, v0 row_mirror row_mask:0xf bank_mask:0xf bound_ctrl:1
	ds_read_b128 v[92:95], v252 offset:20480
	v_add_f32_dpp v78, v78, v78 row_mirror row_mask:0xf bank_mask:0xf bound_ctrl:1
	v_pk_fma_f32 v[166:167], v[108:109], v[0:1], v[166:167] op_sel_hi:[1,0,1]
	v_pk_fma_f32 v[164:165], v[110:111], v[0:1], v[164:165] op_sel_hi:[1,0,1]
	ds_read_b128 v[84:87], v252 offset:12288
	ds_read_b128 v[88:91], v252 offset:36864
	ds_read_b128 v[96:99], v252 offset:4096
	ds_read_b128 v[80:83], v252 offset:28672
	ds_read_b128 v[244:247], v253 offset:41040
	s_waitcnt lgkmcnt(12)
	v_pk_mul_f32 v[248:249], v[166:167], v[120:121]
	v_pk_mul_f32 v[250:251], v[166:167], v[116:117]
	v_pk_fma_f32 v[248:249], v[164:165], v[122:123], v[248:249]
	v_pk_fma_f32 v[250:251], v[164:165], v[118:119], v[250:251]
	v_add_f32_e32 v0, v248, v249
	v_pk_mul_f32 v[202:203], v[238:239], v[208:209] op_sel_hi:[0,1]
	v_add_f32_e32 v79, v250, v251
	v_add_f32_dpp v0, v0, v0 quad_perm:[1,0,3,2] row_mask:0xf bank_mask:0xf bound_ctrl:1
	v_pk_mul_f32 v[128:129], v[238:239], v[210:211] op_sel_hi:[0,1]
	v_add_f32_dpp v79, v79, v79 quad_perm:[1,0,3,2] row_mask:0xf bank_mask:0xf bound_ctrl:1
	v_add_f32_dpp v0, v0, v0 quad_perm:[2,3,0,1] row_mask:0xf bank_mask:0xf bound_ctrl:1
	v_pk_fma_f32 v[166:167], v[166:167], v[124:125], v[202:203]
	v_add_f32_dpp v79, v79, v79 quad_perm:[2,3,0,1] row_mask:0xf bank_mask:0xf bound_ctrl:1
	v_add_f32_dpp v0, v0, v0 row_half_mirror row_mask:0xf bank_mask:0xf bound_ctrl:1
	v_pk_fma_f32 v[164:165], v[164:165], v[126:127], v[128:129]
	v_add_f32_dpp v79, v79, v79 row_half_mirror row_mask:0xf bank_mask:0xf bound_ctrl:1
	v_add_f32_dpp v0, v0, v0 row_mirror row_mask:0xf bank_mask:0xf bound_ctrl:1
	ds_read_b128 v[112:115], v252 offset:20736
	v_add_f32_dpp v79, v79, v79 row_mirror row_mask:0xf bank_mask:0xf bound_ctrl:1
	v_pk_fma_f32 v[166:167], v[204:205], v[0:1], v[166:167] op_sel_hi:[1,0,1]
	v_pk_fma_f32 v[164:165], v[206:207], v[0:1], v[164:165] op_sel_hi:[1,0,1]
	ds_write2_b32 v255, v78, v79 offset0:192 offset1:208
	ds_read_b128 v[104:107], v252 offset:12544
	ds_read_b128 v[108:111], v252 offset:37120
	ds_read_b128 v[116:119], v252 offset:4352
	ds_read_b128 v[100:103], v252 offset:28928
	s_waitcnt lgkmcnt(12)
; #define LAS __attribute__((address_space(3)))
; template <int CTRL> __device__ __forceinline__ float dpp_f(float x) { return __int_as_float(__builtin_amdgcn_update_dpp(0, __float_as_int(x), CTRL, 0xf, 0xf, false)); }
; __device__ __forceinline__ void phase_scan(const Params& p, LAS unsigned char* lds) {
;     ...
;                         for (int u16 = 0; u16 < 16; ++u16) {
;                             const int s = 16 * hb + u16;
;                             const int sn = (s + 1) & 31;
;                             const f32x4 a_n = *(const LAS f32x4*)(sA + sn * 64), w_n = *(const LAS f32x4*)(sW + sn * 64), b_n = *(const LAS f32x4*)(sB + sn * 64);
;                             const f32x4 k_n = *(const LAS f32x4*)(sK + sn * 64), r_n = *(const LAS f32x4*)(sR + sn * 64);
;                             const float v = vq[u16 >> 2][u16 & 3];
;                             const f32x2 vv = {v, v};
;                             f32x2 pp = S01 * (f32x2){a_[0], a_[1]}; pp = S23 * (f32x2){a_[2], a_[3]} + pp;
;                             f32x2 yy = S01 * (f32x2){rp[0], rp[1]}; yy = S23 * (f32x2){rp[2], rp[3]} + yy;
;                             float sa = pp[0] + pp[1], y = yy[0] + yy[1];
;                             sa += dpp_f<0xB1>(sa); y += dpp_f<0xB1>(y);
;                             sa += dpp_f<0x4E>(sa); y += dpp_f<0x4E>(y);
;                             sa += dpp_f<0x141>(sa); y += dpp_f<0x141>(y);
;                             sa += dpp_f<0x140>(sa); y += dpp_f<0x140>(y);
;                             sY[((s - 1) & 31) * 16 + srow] = y;
;                             const f32x2 sv = {sa, sa};
;                             S01 = S01 * (f32x2){w_[0], w_[1]} + vv * (f32x2){k_[0], k_[1]};
;                             S23 = S23 * (f32x2){w_[2], w_[3]} + vv * (f32x2){k_[2], k_[3]};
;                             S01 = sv * (f32x2){b_[0], b_[1]} + S01;
;                             S23 = sv * (f32x2){b_[2], b_[3]} + S23;
;                             rp = r_;
;                             a_ = a_n; w_ = w_n; b_ = b_n; k_ = k_n; r_ = r_n;
;                         }
	v_pk_mul_f32 v[248:249], v[166:167], v[216:217]
	v_pk_mul_f32 v[250:251], v[166:167], v[212:213]
	v_pk_fma_f32 v[248:249], v[164:165], v[218:219], v[248:249]
	v_pk_fma_f32 v[250:251], v[164:165], v[214:215], v[250:251]
	v_add_f32_e32 v0, v248, v249
	v_pk_mul_f32 v[202:203], v[238:239], v[228:229] op_sel:[1,0]
	v_add_f32_e32 v78, v250, v251
	v_add_f32_dpp v0, v0, v0 quad_perm:[1,0,3,2] row_mask:0xf bank_mask:0xf bound_ctrl:1
	v_pk_mul_f32 v[128:129], v[238:239], v[230:231] op_sel:[1,0]
	v_add_f32_dpp v78, v78, v78 quad_perm:[1,0,3,2] row_mask:0xf bank_mask:0xf bound_ctrl:1
	v_add_f32_dpp v0, v0, v0 quad_perm:[2,3,0,1] row_mask:0xf bank_mask:0xf bound_ctrl:1
	v_pk_fma_f32 v[166:167], v[166:167], v[220:221], v[202:203]
	v_add_f32_dpp v78, v78, v78 quad_perm:[2,3,0,1] row_mask:0xf bank_mask:0xf bound_ctrl:1
	v_add_f32_dpp v0, v0, v0 row_half_mirror row_mask:0xf bank_mask:0xf bound_ctrl:1
	v_pk_fma_f32 v[164:165], v[164:165], v[222:223], v[128:129]
	v_add_f32_dpp v78, v78, v78 row_half_mirror row_mask:0xf bank_mask:0xf bound_ctrl:1
	v_add_f32_dpp v0, v0, v0 row_mirror row_mask:0xf bank_mask:0xf bound_ctrl:1
	ds_read_b128 v[208:211], v252 offset:20992
	v_add_f32_dpp v78, v78, v78 row_mirror row_mask:0xf bank_mask:0xf bound_ctrl:1
	v_pk_fma_f32 v[166:167], v[224:225], v[0:1], v[166:167] op_sel_hi:[1,0,1]
	v_pk_fma_f32 v[164:165], v[226:227], v[0:1], v[164:165] op_sel_hi:[1,0,1]
	ds_read_b128 v[124:127], v252 offset:12800
	ds_read_b128 v[204:207], v252 offset:37376
	ds_read_b128 v[212:215], v252 offset:4608
	ds_read_b128 v[120:123], v252 offset:29184
	s_waitcnt lgkmcnt(12)
	v_pk_mul_f32 v[248:249], v[166:167], v[80:81]
	v_pk_mul_f32 v[250:251], v[166:167], v[232:233]
	v_pk_fma_f32 v[248:249], v[164:165], v[82:83], v[248:249]
	v_pk_fma_f32 v[250:251], v[164:165], v[234:235], v[250:251]
	v_add_f32_e32 v0, v248, v249
	v_pk_mul_f32 v[202:203], v[240:241], v[92:93] op_sel_hi:[0,1]
	v_add_f32_e32 v79, v250, v251
	v_add_f32_dpp v0, v0, v0 quad_perm:[1,0,3,2] row_mask:0xf bank_mask:0xf bound_ctrl:1
	v_pk_mul_f32 v[128:129], v[240:241], v[94:95] op_sel_hi:[0,1]
	v_add_f32_dpp v79, v79, v79 quad_perm:[1,0,3,2] row_mask:0xf bank_mask:0xf bound_ctrl:1
	v_add_f32_dpp v0, v0, v0 quad_perm:[2,3,0,1] row_mask:0xf bank_mask:0xf bound_ctrl:1
	v_pk_fma_f32 v[166:167], v[166:167], v[84:85], v[202:203]
	v_add_f32_dpp v79, v79, v79 quad_perm:[2,3,0,1] row_mask:0xf bank_mask:0xf bound_ctrl:1
	v_add_f32_dpp v0, v0, v0 row_half_mirror row_mask:0xf bank_mask:0xf bound_ctrl:1
	v_pk_fma_f32 v[164:165], v[164:165], v[86:87], v[128:129]
	v_add_f32_dpp v79, v79, v79 row_half_mirror row_mask:0xf bank_mask:0xf bound_ctrl:1
	v_add_f32_dpp v0, v0, v0 row_mirror row_mask:0xf bank_mask:0xf bound_ctrl:1
	ds_read_b128 v[228:231], v252 offset:21248
	v_add_f32_dpp v79, v79, v79 row_mirror row_mask:0xf bank_mask:0xf bound_ctrl:1
	v_pk_fma_f32 v[166:167], v[88:89], v[0:1], v[166:167] op_sel_hi:[1,0,1]
	v_pk_fma_f32 v[164:165], v[90:91], v[0:1], v[164:165] op_sel_hi:[1,0,1]
	ds_write2_b32 v255, v78, v79 offset0:224 offset1:240
	v_add_u32_e32 v255, 0x400, v255
	ds_read_b128 v[220:223], v252 offset:13056
	ds_read_b128 v[224:227], v252 offset:37632
	ds_read_b128 v[232:235], v252 offset:4864
	ds_read_b128 v[216:219], v252 offset:29440
	s_waitcnt lgkmcnt(11)
	v_pk_mul_f32 v[248:249], v[166:167], v[100:101]
	v_pk_mul_f32 v[250:251], v[166:167], v[96:97]
	v_pk_fma_f32 v[248:249], v[164:165], v[102:103], v[248:249]
	v_pk_fma_f32 v[250:251], v[164:165], v[98:99], v[250:251]
	v_add_f32_e32 v0, v248, v249
	v_pk_mul_f32 v[202:203], v[240:241], v[112:113] op_sel:[1,0]
	v_add_f32_e32 v78, v250, v251
	v_add_f32_dpp v0, v0, v0 quad_perm:[1,0,3,2] row_mask:0xf bank_mask:0xf bound_ctrl:1
	v_pk_mul_f32 v[128:129], v[240:241], v[114:115] op_sel:[1,0]
	v_add_f32_dpp v78, v78, v78 quad_perm:[1,0,3,2] row_mask:0xf bank_mask:0xf bound_ctrl:1
	v_add_f32_dpp v0, v0, v0 quad_perm:[2,3,0,1] row_mask:0xf bank_mask:0xf bound_ctrl:1
	v_pk_fma_f32 v[166:167], v[166:167], v[104:105], v[202:203]
	v_add_f32_dpp v78, v78, v78 quad_perm:[2,3,0,1] row_mask:0xf bank_mask:0xf bound_ctrl:1
	v_add_f32_dpp v0, v0, v0 row_half_mirror row_mask:0xf bank_mask:0xf bound_ctrl:1
	v_pk_fma_f32 v[164:165], v[164:165], v[106:107], v[128:129]
	v_add_f32_dpp v78, v78, v78 row_half_mirror row_mask:0xf bank_mask:0xf bound_ctrl:1
	v_add_f32_dpp v0, v0, v0 row_mirror row_mask:0xf bank_mask:0xf bound_ctrl:1
	ds_read_b128 v[92:95], v252 offset:21504
	v_add_f32_dpp v78, v78, v78 row_mirror row_mask:0xf bank_mask:0xf bound_ctrl:1
	v_pk_fma_f32 v[166:167], v[108:109], v[0:1], v[166:167] op_sel_hi:[1,0,1]
	v_pk_fma_f32 v[164:165], v[110:111], v[0:1], v[164:165] op_sel_hi:[1,0,1]
	ds_read_b128 v[84:87], v252 offset:13312
	ds_read_b128 v[88:91], v252 offset:37888
	ds_read_b128 v[96:99], v252 offset:5120
	ds_read_b128 v[80:83], v252 offset:29696
	ds_read_b128 v[236:239], v253 offset:41056
	s_waitcnt lgkmcnt(12)
; #define LAS __attribute__((address_space(3)))
; template <int CTRL> __device__ __forceinline__ float dpp_f(float x) { return __int_as_float(__builtin_amdgcn_update_dpp(0, __float_as_int(x), CTRL, 0xf, 0xf, false)); }
; __device__ __forceinline__ void phase_scan(const Params& p, LAS unsigned char* lds) {
;     ...
;                         for (int u16 = 0; u16 < 16; ++u16) {
;                             const int s = 16 * hb + u16;
;                             const int sn = (s + 1) & 31;
;                             const f32x4 a_n = *(const LAS f32x4*)(sA + sn * 64), w_n = *(const LAS f32x4*)(sW + sn * 64), b_n = *(const LAS f32x4*)(sB + sn * 64);
;                             const f32x4 k_n = *(const LAS f32x4*)(sK + sn * 64), r_n = *(const LAS f32x4*)(sR + sn * 64);
;                             const float v = vq[u16 >> 2][u16 & 3];
;                             const f32x2 vv = {v, v};
;                             f32x2 pp = S01 * (f32x2){a_[0], a_[1]}; pp = S23 * (f32x2){a_[2], a_[3]} + pp;
;                             f32x2 yy = S01 * (f32x2){rp[0], rp[1]}; yy = S23 * (f32x2){rp[2], rp[3]} + yy;
;                             float sa = pp[0] + pp[1], y = yy[0] + yy[1];
;                             sa += dpp_f<0xB1>(sa); y += dpp_f<0xB1>(y);
;                             sa += dpp_f<0x4E>(sa); y += dpp_f<0x4E>(y);
;                             sa += dpp_f<0x141>(sa); y += dpp_f<0x141>(y);
;                             sa += dpp_f<0x140>(sa); y += dpp_f<0x140>(y);
;                             sY[((s - 1) & 31) * 16 + srow] = y;
;                             const f32x2 sv = {sa, sa};
;                             S01 = S01 * (f32x2){w_[0], w_[1]} + vv * (f32x2){k_[0], k_[1]};
;                             S23 = S23 * (f32x2){w_[2], w_[3]} + vv * (f32x2){k_[2], k_[3]};
;                             S01 = sv * (f32x2){b_[0], b_[1]} + S01;
;                             S23 = sv * (f32x2){b_[2], b_[3]} + S23;
;                             rp = r_;
;                             a_ = a_n; w_ = w_n; b_ = b_n; k_ = k_n; r_ = r_n;
;                         }
	v_pk_mul_f32 v[248:249], v[166:167], v[120:121]
	v_pk_mul_f32 v[250:251], v[166:167], v[116:117]
	v_pk_fma_f32 v[248:249], v[164:165], v[122:123], v[248:249]
	v_pk_fma_f32 v[250:251], v[164:165], v[118:119], v[250:251]
	v_add_f32_e32 v0, v248, v249
	v_pk_mul_f32 v[202:203], v[242:243], v[208:209] op_sel_hi:[0,1]
	v_add_f32_e32 v79, v250, v251
	v_add_f32_dpp v0, v0, v0 quad_perm:[1,0,3,2] row_mask:0xf bank_mask:0xf bound_ctrl:1
	v_pk_mul_f32 v[128:129], v[242:243], v[210:211] op_sel_hi:[0,1]
	v_add_f32_dpp v79, v79, v79 quad_perm:[1,0,3,2] row_mask:0xf bank_mask:0xf bound_ctrl:1
	v_add_f32_dpp v0, v0, v0 quad_perm:[2,3,0,1] row_mask:0xf bank_mask:0xf bound_ctrl:1
	v_pk_fma_f32 v[166:167], v[166:167], v[124:125], v[202:203]
	v_add_f32_dpp v79, v79, v79 quad_perm:[2,3,0,1] row_mask:0xf bank_mask:0xf bound_ctrl:1
	v_add_f32_dpp v0, v0, v0 row_half_mirror row_mask:0xf bank_mask:0xf bound_ctrl:1
	v_pk_fma_f32 v[164:165], v[164:165], v[126:127], v[128:129]
	v_add_f32_dpp v79, v79, v79 row_half_mirror row_mask:0xf bank_mask:0xf bound_ctrl:1
	v_add_f32_dpp v0, v0, v0 row_mirror row_mask:0xf bank_mask:0xf bound_ctrl:1
	ds_read_b128 v[112:115], v252 offset:21760
	v_add_f32_dpp v79, v79, v79 row_mirror row_mask:0xf bank_mask:0xf bound_ctrl:1
	v_pk_fma_f32 v[166:167], v[204:205], v[0:1], v[166:167] op_sel_hi:[1,0,1]
	v_pk_fma_f32 v[164:165], v[206:207], v[0:1], v[164:165] op_sel_hi:[1,0,1]
	ds_write2_b32 v255, v78, v79 offset1:16
	ds_read_b128 v[104:107], v252 offset:13568
	ds_read_b128 v[108:111], v252 offset:38144
	ds_read_b128 v[116:119], v252 offset:5376
	ds_read_b128 v[100:103], v252 offset:29952
	s_waitcnt lgkmcnt(12)
	v_pk_mul_f32 v[248:249], v[166:167], v[216:217]
	v_pk_mul_f32 v[250:251], v[166:167], v[212:213]
	v_pk_fma_f32 v[248:249], v[164:165], v[218:219], v[248:249]
	v_pk_fma_f32 v[250:251], v[164:165], v[214:215], v[250:251]
	v_add_f32_e32 v0, v248, v249
	v_pk_mul_f32 v[202:203], v[242:243], v[228:229] op_sel:[1,0]
	v_add_f32_e32 v78, v250, v251
	v_add_f32_dpp v0, v0, v0 quad_perm:[1,0,3,2] row_mask:0xf bank_mask:0xf bound_ctrl:1
	v_pk_mul_f32 v[128:129], v[242:243], v[230:231] op_sel:[1,0]
	v_add_f32_dpp v78, v78, v78 quad_perm:[1,0,3,2] row_mask:0xf bank_mask:0xf bound_ctrl:1
	v_add_f32_dpp v0, v0, v0 quad_perm:[2,3,0,1] row_mask:0xf bank_mask:0xf bound_ctrl:1
	v_pk_fma_f32 v[166:167], v[166:167], v[220:221], v[202:203]
	v_add_f32_dpp v78, v78, v78 quad_perm:[2,3,0,1] row_mask:0xf bank_mask:0xf bound_ctrl:1
	v_add_f32_dpp v0, v0, v0 row_half_mirror row_mask:0xf bank_mask:0xf bound_ctrl:1
	v_pk_fma_f32 v[164:165], v[164:165], v[222:223], v[128:129]
	v_add_f32_dpp v78, v78, v78 row_half_mirror row_mask:0xf bank_mask:0xf bound_ctrl:1
	v_add_f32_dpp v0, v0, v0 row_mirror row_mask:0xf bank_mask:0xf bound_ctrl:1
	ds_read_b128 v[208:211], v252 offset:22016
	v_add_f32_dpp v78, v78, v78 row_mirror row_mask:0xf bank_mask:0xf bound_ctrl:1
	v_pk_fma_f32 v[166:167], v[224:225], v[0:1], v[166:167] op_sel_hi:[1,0,1]
	v_pk_fma_f32 v[164:165], v[226:227], v[0:1], v[164:165] op_sel_hi:[1,0,1]
	ds_read_b128 v[124:127], v252 offset:13824
	ds_read_b128 v[204:207], v252 offset:38400
	ds_read_b128 v[212:215], v252 offset:5632
	ds_read_b128 v[120:123], v252 offset:30208
	s_waitcnt lgkmcnt(12)
	v_pk_mul_f32 v[248:249], v[166:167], v[80:81]
	v_pk_mul_f32 v[250:251], v[166:167], v[232:233]
	v_pk_fma_f32 v[248:249], v[164:165], v[82:83], v[248:249]
	v_pk_fma_f32 v[250:251], v[164:165], v[234:235], v[250:251]
	v_add_f32_e32 v0, v248, v249
	v_pk_mul_f32 v[202:203], v[244:245], v[92:93] op_sel_hi:[0,1]
	v_add_f32_e32 v79, v250, v251
	v_add_f32_dpp v0, v0, v0 quad_perm:[1,0,3,2] row_mask:0xf bank_mask:0xf bound_ctrl:1
	v_pk_mul_f32 v[128:129], v[244:245], v[94:95] op_sel_hi:[0,1]
	v_add_f32_dpp v79, v79, v79 quad_perm:[1,0,3,2] row_mask:0xf bank_mask:0xf bound_ctrl:1
	v_add_f32_dpp v0, v0, v0 quad_perm:[2,3,0,1] row_mask:0xf bank_mask:0xf bound_ctrl:1
	v_pk_fma_f32 v[166:167], v[166:167], v[84:85], v[202:203]
	v_add_f32_dpp v79, v79, v79 quad_perm:[2,3,0,1] row_mask:0xf bank_mask:0xf bound_ctrl:1
	v_add_f32_dpp v0, v0, v0 row_half_mirror row_mask:0xf bank_mask:0xf bound_ctrl:1
	v_pk_fma_f32 v[164:165], v[164:165], v[86:87], v[128:129]
	v_add_f32_dpp v79, v79, v79 row_half_mirror row_mask:0xf bank_mask:0xf bound_ctrl:1
	v_add_f32_dpp v0, v0, v0 row_mirror row_mask:0xf bank_mask:0xf bound_ctrl:1
	ds_read_b128 v[228:231], v252 offset:22272
	v_add_f32_dpp v79, v79, v79 row_mirror row_mask:0xf bank_mask:0xf bound_ctrl:1
	v_pk_fma_f32 v[166:167], v[88:89], v[0:1], v[166:167] op_sel_hi:[1,0,1]
	v_pk_fma_f32 v[164:165], v[90:91], v[0:1], v[164:165] op_sel_hi:[1,0,1]
	ds_write2_b32 v255, v78, v79 offset0:32 offset1:48
	ds_read_b128 v[220:223], v252 offset:14080
	ds_read_b128 v[224:227], v252 offset:38656
	ds_read_b128 v[232:235], v252 offset:5888
	ds_read_b128 v[216:219], v252 offset:30464
	s_waitcnt lgkmcnt(11)
; #define LAS __attribute__((address_space(3)))
; template <int CTRL> __device__ __forceinline__ float dpp_f(float x) { return __int_as_float(__builtin_amdgcn_update_dpp(0, __float_as_int(x), CTRL, 0xf, 0xf, false)); }
; __device__ __forceinline__ void phase_scan(const Params& p, LAS unsigned char* lds) {
;     ...
;                         for (int u16 = 0; u16 < 16; ++u16) {
;                             const int s = 16 * hb + u16;
;                             const int sn = (s + 1) & 31;
;                             const f32x4 a_n = *(const LAS f32x4*)(sA + sn * 64), w_n = *(const LAS f32x4*)(sW + sn * 64), b_n = *(const LAS f32x4*)(sB + sn * 64);
;                             const f32x4 k_n = *(const LAS f32x4*)(sK + sn * 64), r_n = *(const LAS f32x4*)(sR + sn * 64);
;                             const float v = vq[u16 >> 2][u16 & 3];
;                             const f32x2 vv = {v, v};
;                             f32x2 pp = S01 * (f32x2){a_[0], a_[1]}; pp = S23 * (f32x2){a_[2], a_[3]} + pp;
;                             f32x2 yy = S01 * (f32x2){rp[0], rp[1]}; yy = S23 * (f32x2){rp[2], rp[3]} + yy;
;                             float sa = pp[0] + pp[1], y = yy[0] + yy[1];
;                             sa += dpp_f<0xB1>(sa); y += dpp_f<0xB1>(y);
;                             sa += dpp_f<0x4E>(sa); y += dpp_f<0x4E>(y);
;                             sa += dpp_f<0x141>(sa); y += dpp_f<0x141>(y);
;                             sa += dpp_f<0x140>(sa); y += dpp_f<0x140>(y);
;                             sY[((s - 1) & 31) * 16 + srow] = y;
;                             const f32x2 sv = {sa, sa};
;                             S01 = S01 * (f32x2){w_[0], w_[1]} + vv * (f32x2){k_[0], k_[1]};
;                             S23 = S23 * (f32x2){w_[2], w_[3]} + vv * (f32x2){k_[2], k_[3]};
;                             S01 = sv * (f32x2){b_[0], b_[1]} + S01;
;                             S23 = sv * (f32x2){b_[2], b_[3]} + S23;
;                             rp = r_;
;                             a_ = a_n; w_ = w_n; b_ = b_n; k_ = k_n; r_ = r_n;
;                         }
	v_pk_mul_f32 v[248:249], v[166:167], v[100:101]
	v_pk_mul_f32 v[250:251], v[166:167], v[96:97]
	v_pk_fma_f32 v[248:249], v[164:165], v[102:103], v[248:249]
	v_pk_fma_f32 v[250:251], v[164:165], v[98:99], v[250:251]
	v_add_f32_e32 v0, v248, v249
	v_pk_mul_f32 v[202:203], v[244:245], v[112:113] op_sel:[1,0]
	v_add_f32_e32 v78, v250, v251
	v_add_f32_dpp v0, v0, v0 quad_perm:[1,0,3,2] row_mask:0xf bank_mask:0xf bound_ctrl:1
	v_pk_mul_f32 v[128:129], v[244:245], v[114:115] op_sel:[1,0]
	v_add_f32_dpp v78, v78, v78 quad_perm:[1,0,3,2] row_mask:0xf bank_mask:0xf bound_ctrl:1
	v_add_f32_dpp v0, v0, v0 quad_perm:[2,3,0,1] row_mask:0xf bank_mask:0xf bound_ctrl:1
	v_pk_fma_f32 v[166:167], v[166:167], v[104:105], v[202:203]
	v_add_f32_dpp v78, v78, v78 quad_perm:[2,3,0,1] row_mask:0xf bank_mask:0xf bound_ctrl:1
	v_add_f32_dpp v0, v0, v0 row_half_mirror row_mask:0xf bank_mask:0xf bound_ctrl:1
	v_pk_fma_f32 v[164:165], v[164:165], v[106:107], v[128:129]
	v_add_f32_dpp v78, v78, v78 row_half_mirror row_mask:0xf bank_mask:0xf bound_ctrl:1
	v_add_f32_dpp v0, v0, v0 row_mirror row_mask:0xf bank_mask:0xf bound_ctrl:1
	ds_read_b128 v[92:95], v252 offset:22528
	v_add_f32_dpp v78, v78, v78 row_mirror row_mask:0xf bank_mask:0xf bound_ctrl:1
	v_pk_fma_f32 v[166:167], v[108:109], v[0:1], v[166:167] op_sel_hi:[1,0,1]
	v_pk_fma_f32 v[164:165], v[110:111], v[0:1], v[164:165] op_sel_hi:[1,0,1]
	ds_read_b128 v[84:87], v252 offset:14336
	ds_read_b128 v[88:91], v252 offset:38912
	ds_read_b128 v[96:99], v252 offset:6144
	ds_read_b128 v[80:83], v252 offset:30720
	ds_read_b128 v[240:243], v253 offset:41072
	s_waitcnt lgkmcnt(12)
	v_pk_mul_f32 v[248:249], v[166:167], v[120:121]
	v_pk_mul_f32 v[250:251], v[166:167], v[116:117]
	v_pk_fma_f32 v[248:249], v[164:165], v[122:123], v[248:249]
	v_pk_fma_f32 v[250:251], v[164:165], v[118:119], v[250:251]
	v_add_f32_e32 v0, v248, v249
	v_pk_mul_f32 v[202:203], v[246:247], v[208:209] op_sel_hi:[0,1]
	v_add_f32_e32 v79, v250, v251
	v_add_f32_dpp v0, v0, v0 quad_perm:[1,0,3,2] row_mask:0xf bank_mask:0xf bound_ctrl:1
	v_pk_mul_f32 v[128:129], v[246:247], v[210:211] op_sel_hi:[0,1]
	v_add_f32_dpp v79, v79, v79 quad_perm:[1,0,3,2] row_mask:0xf bank_mask:0xf bound_ctrl:1
	v_add_f32_dpp v0, v0, v0 quad_perm:[2,3,0,1] row_mask:0xf bank_mask:0xf bound_ctrl:1
	v_pk_fma_f32 v[166:167], v[166:167], v[124:125], v[202:203]
	v_add_f32_dpp v79, v79, v79 quad_perm:[2,3,0,1] row_mask:0xf bank_mask:0xf bound_ctrl:1
	v_add_f32_dpp v0, v0, v0 row_half_mirror row_mask:0xf bank_mask:0xf bound_ctrl:1
	v_pk_fma_f32 v[164:165], v[164:165], v[126:127], v[128:129]
	v_add_f32_dpp v79, v79, v79 row_half_mirror row_mask:0xf bank_mask:0xf bound_ctrl:1
	v_add_f32_dpp v0, v0, v0 row_mirror row_mask:0xf bank_mask:0xf bound_ctrl:1
	ds_read_b128 v[112:115], v252 offset:22784
	v_add_f32_dpp v79, v79, v79 row_mirror row_mask:0xf bank_mask:0xf bound_ctrl:1
	v_pk_fma_f32 v[166:167], v[204:205], v[0:1], v[166:167] op_sel_hi:[1,0,1]
	v_pk_fma_f32 v[164:165], v[206:207], v[0:1], v[164:165] op_sel_hi:[1,0,1]
	ds_write2_b32 v255, v78, v79 offset0:64 offset1:80
	ds_read_b128 v[104:107], v252 offset:14592
	ds_read_b128 v[108:111], v252 offset:39168
	ds_read_b128 v[116:119], v252 offset:6400
	ds_read_b128 v[100:103], v252 offset:30976
	s_waitcnt lgkmcnt(12)
	v_pk_mul_f32 v[248:249], v[166:167], v[216:217]
	v_pk_mul_f32 v[250:251], v[166:167], v[212:213]
	v_pk_fma_f32 v[248:249], v[164:165], v[218:219], v[248:249]
	v_pk_fma_f32 v[250:251], v[164:165], v[214:215], v[250:251]
	v_add_f32_e32 v0, v248, v249
	v_pk_mul_f32 v[202:203], v[246:247], v[228:229] op_sel:[1,0]
	v_add_f32_e32 v78, v250, v251
	v_add_f32_dpp v0, v0, v0 quad_perm:[1,0,3,2] row_mask:0xf bank_mask:0xf bound_ctrl:1
	v_pk_mul_f32 v[128:129], v[246:247], v[230:231] op_sel:[1,0]
	v_add_f32_dpp v78, v78, v78 quad_perm:[1,0,3,2] row_mask:0xf bank_mask:0xf bound_ctrl:1
	v_add_f32_dpp v0, v0, v0 quad_perm:[2,3,0,1] row_mask:0xf bank_mask:0xf bound_ctrl:1
	v_pk_fma_f32 v[166:167], v[166:167], v[220:221], v[202:203]
	v_add_f32_dpp v78, v78, v78 quad_perm:[2,3,0,1] row_mask:0xf bank_mask:0xf bound_ctrl:1
	v_add_f32_dpp v0, v0, v0 row_half_mirror row_mask:0xf bank_mask:0xf bound_ctrl:1
	v_pk_fma_f32 v[164:165], v[164:165], v[222:223], v[128:129]
	v_add_f32_dpp v78, v78, v78 row_half_mirror row_mask:0xf bank_mask:0xf bound_ctrl:1
	v_add_f32_dpp v0, v0, v0 row_mirror row_mask:0xf bank_mask:0xf bound_ctrl:1
	ds_read_b128 v[208:211], v252 offset:23040
	v_add_f32_dpp v78, v78, v78 row_mirror row_mask:0xf bank_mask:0xf bound_ctrl:1
	v_pk_fma_f32 v[166:167], v[224:225], v[0:1], v[166:167] op_sel_hi:[1,0,1]
	v_pk_fma_f32 v[164:165], v[226:227], v[0:1], v[164:165] op_sel_hi:[1,0,1]
	ds_read_b128 v[124:127], v252 offset:14848
	ds_read_b128 v[204:207], v252 offset:39424
	ds_read_b128 v[212:215], v252 offset:6656
	ds_read_b128 v[120:123], v252 offset:31232
	s_waitcnt lgkmcnt(12)
; #define LAS __attribute__((address_space(3)))
; template <int CTRL> __device__ __forceinline__ float dpp_f(float x) { return __int_as_float(__builtin_amdgcn_update_dpp(0, __float_as_int(x), CTRL, 0xf, 0xf, false)); }
; __device__ __forceinline__ void phase_scan(const Params& p, LAS unsigned char* lds) {
;     ...
;                         for (int u16 = 0; u16 < 16; ++u16) {
;                             const int s = 16 * hb + u16;
;                             const int sn = (s + 1) & 31;
;                             const f32x4 a_n = *(const LAS f32x4*)(sA + sn * 64), w_n = *(const LAS f32x4*)(sW + sn * 64), b_n = *(const LAS f32x4*)(sB + sn * 64);
;                             const f32x4 k_n = *(const LAS f32x4*)(sK + sn * 64), r_n = *(const LAS f32x4*)(sR + sn * 64);
;                             const float v = vq[u16 >> 2][u16 & 3];
;                             const f32x2 vv = {v, v};
;                             f32x2 pp = S01 * (f32x2){a_[0], a_[1]}; pp = S23 * (f32x2){a_[2], a_[3]} + pp;
;                             f32x2 yy = S01 * (f32x2){rp[0], rp[1]}; yy = S23 * (f32x2){rp[2], rp[3]} + yy;
;                             float sa = pp[0] + pp[1], y = yy[0] + yy[1];
;                             sa += dpp_f<0xB1>(sa); y += dpp_f<0xB1>(y);
;                             sa += dpp_f<0x4E>(sa); y += dpp_f<0x4E>(y);
;                             sa += dpp_f<0x141>(sa); y += dpp_f<0x141>(y);
;                             sa += dpp_f<0x140>(sa); y += dpp_f<0x140>(y);
;                             sY[((s - 1) & 31) * 16 + srow] = y;
;                             const f32x2 sv = {sa, sa};
;                             S01 = S01 * (f32x2){w_[0], w_[1]} + vv * (f32x2){k_[0], k_[1]};
;                             S23 = S23 * (f32x2){w_[2], w_[3]} + vv * (f32x2){k_[2], k_[3]};
;                             S01 = sv * (f32x2){b_[0], b_[1]} + S01;
;                             S23 = sv * (f32x2){b_[2], b_[3]} + S23;
;                             rp = r_;
;                             a_ = a_n; w_ = w_n; b_ = b_n; k_ = k_n; r_ = r_n;
;                         }
	v_pk_mul_f32 v[248:249], v[166:167], v[80:81]
	v_pk_mul_f32 v[250:251], v[166:167], v[232:233]
	v_pk_fma_f32 v[248:249], v[164:165], v[82:83], v[248:249]
	v_pk_fma_f32 v[250:251], v[164:165], v[234:235], v[250:251]
	v_add_f32_e32 v0, v248, v249
	v_pk_mul_f32 v[202:203], v[236:237], v[92:93] op_sel_hi:[0,1]
	v_add_f32_e32 v79, v250, v251
	v_add_f32_dpp v0, v0, v0 quad_perm:[1,0,3,2] row_mask:0xf bank_mask:0xf bound_ctrl:1
	v_pk_mul_f32 v[128:129], v[236:237], v[94:95] op_sel_hi:[0,1]
	v_add_f32_dpp v79, v79, v79 quad_perm:[1,0,3,2] row_mask:0xf bank_mask:0xf bound_ctrl:1
	v_add_f32_dpp v0, v0, v0 quad_perm:[2,3,0,1] row_mask:0xf bank_mask:0xf bound_ctrl:1
	v_pk_fma_f32 v[166:167], v[166:167], v[84:85], v[202:203]
	v_add_f32_dpp v79, v79, v79 quad_perm:[2,3,0,1] row_mask:0xf bank_mask:0xf bound_ctrl:1
	v_add_f32_dpp v0, v0, v0 row_half_mirror row_mask:0xf bank_mask:0xf bound_ctrl:1
	v_pk_fma_f32 v[164:165], v[164:165], v[86:87], v[128:129]
	v_add_f32_dpp v79, v79, v79 row_half_mirror row_mask:0xf bank_mask:0xf bound_ctrl:1
	v_add_f32_dpp v0, v0, v0 row_mirror row_mask:0xf bank_mask:0xf bound_ctrl:1
	ds_read_b128 v[228:231], v252 offset:23296
	v_add_f32_dpp v79, v79, v79 row_mirror row_mask:0xf bank_mask:0xf bound_ctrl:1
	v_pk_fma_f32 v[166:167], v[88:89], v[0:1], v[166:167] op_sel_hi:[1,0,1]
	v_pk_fma_f32 v[164:165], v[90:91], v[0:1], v[164:165] op_sel_hi:[1,0,1]
	ds_write2_b32 v255, v78, v79 offset0:96 offset1:112
	ds_read_b128 v[220:223], v252 offset:15104
	ds_read_b128 v[224:227], v252 offset:39680
	ds_read_b128 v[232:235], v252 offset:6912
	ds_read_b128 v[216:219], v252 offset:31488
	s_waitcnt lgkmcnt(11)
	v_pk_mul_f32 v[248:249], v[166:167], v[100:101]
	v_pk_mul_f32 v[250:251], v[166:167], v[96:97]
	v_pk_fma_f32 v[248:249], v[164:165], v[102:103], v[248:249]
	v_pk_fma_f32 v[250:251], v[164:165], v[98:99], v[250:251]
	v_add_f32_e32 v0, v248, v249
	v_pk_mul_f32 v[202:203], v[236:237], v[112:113] op_sel:[1,0]
	v_add_f32_e32 v78, v250, v251
	v_add_f32_dpp v0, v0, v0 quad_perm:[1,0,3,2] row_mask:0xf bank_mask:0xf bound_ctrl:1
	v_pk_mul_f32 v[128:129], v[236:237], v[114:115] op_sel:[1,0]
	v_add_f32_dpp v78, v78, v78 quad_perm:[1,0,3,2] row_mask:0xf bank_mask:0xf bound_ctrl:1
	v_add_f32_dpp v0, v0, v0 quad_perm:[2,3,0,1] row_mask:0xf bank_mask:0xf bound_ctrl:1
	v_pk_fma_f32 v[166:167], v[166:167], v[104:105], v[202:203]
	v_add_f32_dpp v78, v78, v78 quad_perm:[2,3,0,1] row_mask:0xf bank_mask:0xf bound_ctrl:1
	v_add_f32_dpp v0, v0, v0 row_half_mirror row_mask:0xf bank_mask:0xf bound_ctrl:1
	v_pk_fma_f32 v[164:165], v[164:165], v[106:107], v[128:129]
	v_add_f32_dpp v78, v78, v78 row_half_mirror row_mask:0xf bank_mask:0xf bound_ctrl:1
	v_add_f32_dpp v0, v0, v0 row_mirror row_mask:0xf bank_mask:0xf bound_ctrl:1
	ds_read_b128 v[92:95], v252 offset:23552
	v_add_f32_dpp v78, v78, v78 row_mirror row_mask:0xf bank_mask:0xf bound_ctrl:1
	v_pk_fma_f32 v[166:167], v[108:109], v[0:1], v[166:167] op_sel_hi:[1,0,1]
	v_pk_fma_f32 v[164:165], v[110:111], v[0:1], v[164:165] op_sel_hi:[1,0,1]
	ds_read_b128 v[84:87], v252 offset:15360
	ds_read_b128 v[88:91], v252 offset:39936
	ds_read_b128 v[96:99], v252 offset:7168
	ds_read_b128 v[80:83], v252 offset:31744
	s_waitcnt lgkmcnt(11)
	v_pk_mul_f32 v[248:249], v[166:167], v[120:121]
	v_pk_mul_f32 v[250:251], v[166:167], v[116:117]
	v_pk_fma_f32 v[248:249], v[164:165], v[122:123], v[248:249]
	v_pk_fma_f32 v[250:251], v[164:165], v[118:119], v[250:251]
	v_add_f32_e32 v0, v248, v249
	v_pk_mul_f32 v[202:203], v[238:239], v[208:209] op_sel_hi:[0,1]
	v_add_f32_e32 v79, v250, v251
	v_add_f32_dpp v0, v0, v0 quad_perm:[1,0,3,2] row_mask:0xf bank_mask:0xf bound_ctrl:1
	v_pk_mul_f32 v[128:129], v[238:239], v[210:211] op_sel_hi:[0,1]
	v_add_f32_dpp v79, v79, v79 quad_perm:[1,0,3,2] row_mask:0xf bank_mask:0xf bound_ctrl:1
	v_add_f32_dpp v0, v0, v0 quad_perm:[2,3,0,1] row_mask:0xf bank_mask:0xf bound_ctrl:1
	v_pk_fma_f32 v[166:167], v[166:167], v[124:125], v[202:203]
	v_add_f32_dpp v79, v79, v79 quad_perm:[2,3,0,1] row_mask:0xf bank_mask:0xf bound_ctrl:1
	v_add_f32_dpp v0, v0, v0 row_half_mirror row_mask:0xf bank_mask:0xf bound_ctrl:1
	v_pk_fma_f32 v[164:165], v[164:165], v[126:127], v[128:129]
	v_add_f32_dpp v79, v79, v79 row_half_mirror row_mask:0xf bank_mask:0xf bound_ctrl:1
	v_add_f32_dpp v0, v0, v0 row_mirror row_mask:0xf bank_mask:0xf bound_ctrl:1
	ds_read_b128 v[112:115], v252 offset:23808
	v_add_f32_dpp v79, v79, v79 row_mirror row_mask:0xf bank_mask:0xf bound_ctrl:1
	v_pk_fma_f32 v[166:167], v[204:205], v[0:1], v[166:167] op_sel_hi:[1,0,1]
	v_pk_fma_f32 v[164:165], v[206:207], v[0:1], v[164:165] op_sel_hi:[1,0,1]
	ds_write2_b32 v255, v78, v79 offset0:128 offset1:144
	ds_read_b128 v[104:107], v252 offset:15616
	ds_read_b128 v[108:111], v252 offset:40192
	ds_read_b128 v[116:119], v252 offset:7424
	ds_read_b128 v[100:103], v252 offset:32000
	s_waitcnt lgkmcnt(11)
; #define LAS __attribute__((address_space(3)))
; template <int CTRL> __device__ __forceinline__ float dpp_f(float x) { return __int_as_float(__builtin_amdgcn_update_dpp(0, __float_as_int(x), CTRL, 0xf, 0xf, false)); }
; __device__ __forceinline__ void phase_scan(const Params& p, LAS unsigned char* lds) {
;     ...
;                         for (int u16 = 0; u16 < 16; ++u16) {
;                             const int s = 16 * hb + u16;
;                             const int sn = (s + 1) & 31;
;                             const f32x4 a_n = *(const LAS f32x4*)(sA + sn * 64), w_n = *(const LAS f32x4*)(sW + sn * 64), b_n = *(const LAS f32x4*)(sB + sn * 64);
;                             const f32x4 k_n = *(const LAS f32x4*)(sK + sn * 64), r_n = *(const LAS f32x4*)(sR + sn * 64);
;                             const float v = vq[u16 >> 2][u16 & 3];
;                             const f32x2 vv = {v, v};
;                             f32x2 pp = S01 * (f32x2){a_[0], a_[1]}; pp = S23 * (f32x2){a_[2], a_[3]} + pp;
;                             f32x2 yy = S01 * (f32x2){rp[0], rp[1]}; yy = S23 * (f32x2){rp[2], rp[3]} + yy;
;                             float sa = pp[0] + pp[1], y = yy[0] + yy[1];
;                             sa += dpp_f<0xB1>(sa); y += dpp_f<0xB1>(y);
;                             sa += dpp_f<0x4E>(sa); y += dpp_f<0x4E>(y);
;                             sa += dpp_f<0x141>(sa); y += dpp_f<0x141>(y);
;                             sa += dpp_f<0x140>(sa); y += dpp_f<0x140>(y);
;                             sY[((s - 1) & 31) * 16 + srow] = y;
;                             const f32x2 sv = {sa, sa};
;                             S01 = S01 * (f32x2){w_[0], w_[1]} + vv * (f32x2){k_[0], k_[1]};
;                             S23 = S23 * (f32x2){w_[2], w_[3]} + vv * (f32x2){k_[2], k_[3]};
;                             S01 = sv * (f32x2){b_[0], b_[1]} + S01;
;                             S23 = sv * (f32x2){b_[2], b_[3]} + S23;
;                             rp = r_;
;                             a_ = a_n; w_ = w_n; b_ = b_n; k_ = k_n; r_ = r_n;
;                         }
	v_pk_mul_f32 v[248:249], v[166:167], v[216:217]
	v_pk_mul_f32 v[250:251], v[166:167], v[212:213]
	v_pk_fma_f32 v[248:249], v[164:165], v[218:219], v[248:249]
	v_pk_fma_f32 v[250:251], v[164:165], v[214:215], v[250:251]
	v_add_f32_e32 v0, v248, v249
	v_pk_mul_f32 v[202:203], v[238:239], v[228:229] op_sel:[1,0]
	v_add_f32_e32 v78, v250, v251
	v_add_f32_dpp v0, v0, v0 quad_perm:[1,0,3,2] row_mask:0xf bank_mask:0xf bound_ctrl:1
	v_pk_mul_f32 v[128:129], v[238:239], v[230:231] op_sel:[1,0]
	v_add_f32_dpp v78, v78, v78 quad_perm:[1,0,3,2] row_mask:0xf bank_mask:0xf bound_ctrl:1
	v_add_f32_dpp v0, v0, v0 quad_perm:[2,3,0,1] row_mask:0xf bank_mask:0xf bound_ctrl:1
	v_pk_fma_f32 v[166:167], v[166:167], v[220:221], v[202:203]
	v_add_f32_dpp v78, v78, v78 quad_perm:[2,3,0,1] row_mask:0xf bank_mask:0xf bound_ctrl:1
	v_add_f32_dpp v0, v0, v0 row_half_mirror row_mask:0xf bank_mask:0xf bound_ctrl:1
	v_pk_fma_f32 v[164:165], v[164:165], v[222:223], v[128:129]
	v_add_f32_dpp v78, v78, v78 row_half_mirror row_mask:0xf bank_mask:0xf bound_ctrl:1
	v_add_f32_dpp v0, v0, v0 row_mirror row_mask:0xf bank_mask:0xf bound_ctrl:1
	ds_read_b128 v[208:211], v252 offset:24064
	v_add_f32_dpp v78, v78, v78 row_mirror row_mask:0xf bank_mask:0xf bound_ctrl:1
	v_pk_fma_f32 v[166:167], v[224:225], v[0:1], v[166:167] op_sel_hi:[1,0,1]
	v_pk_fma_f32 v[164:165], v[226:227], v[0:1], v[164:165] op_sel_hi:[1,0,1]
	ds_read_b128 v[124:127], v252 offset:15872
	ds_read_b128 v[204:207], v252 offset:40448
	ds_read_b128 v[212:215], v252 offset:7680
	ds_read_b128 v[120:123], v252 offset:32256
	s_waitcnt lgkmcnt(11)
	v_pk_mul_f32 v[248:249], v[166:167], v[80:81]
	v_pk_mul_f32 v[250:251], v[166:167], v[232:233]
	v_pk_fma_f32 v[248:249], v[164:165], v[82:83], v[248:249]
	v_pk_fma_f32 v[250:251], v[164:165], v[234:235], v[250:251]
	v_add_f32_e32 v0, v248, v249
	v_pk_mul_f32 v[202:203], v[240:241], v[92:93] op_sel_hi:[0,1]
	v_add_f32_e32 v79, v250, v251
	v_add_f32_dpp v0, v0, v0 quad_perm:[1,0,3,2] row_mask:0xf bank_mask:0xf bound_ctrl:1
	v_pk_mul_f32 v[128:129], v[240:241], v[94:95] op_sel_hi:[0,1]
	v_add_f32_dpp v79, v79, v79 quad_perm:[1,0,3,2] row_mask:0xf bank_mask:0xf bound_ctrl:1
	v_add_f32_dpp v0, v0, v0 quad_perm:[2,3,0,1] row_mask:0xf bank_mask:0xf bound_ctrl:1
	v_pk_fma_f32 v[166:167], v[166:167], v[84:85], v[202:203]
	v_add_f32_dpp v79, v79, v79 quad_perm:[2,3,0,1] row_mask:0xf bank_mask:0xf bound_ctrl:1
	v_add_f32_dpp v0, v0, v0 row_half_mirror row_mask:0xf bank_mask:0xf bound_ctrl:1
	v_pk_fma_f32 v[164:165], v[164:165], v[86:87], v[128:129]
	v_add_f32_dpp v79, v79, v79 row_half_mirror row_mask:0xf bank_mask:0xf bound_ctrl:1
	v_add_f32_dpp v0, v0, v0 row_mirror row_mask:0xf bank_mask:0xf bound_ctrl:1
	ds_read_b128 v[228:231], v252 offset:24320
	v_add_f32_dpp v79, v79, v79 row_mirror row_mask:0xf bank_mask:0xf bound_ctrl:1
	v_pk_fma_f32 v[166:167], v[88:89], v[0:1], v[166:167] op_sel_hi:[1,0,1]
	v_pk_fma_f32 v[164:165], v[90:91], v[0:1], v[164:165] op_sel_hi:[1,0,1]
	ds_write2_b32 v255, v78, v79 offset0:160 offset1:176
	ds_read_b128 v[220:223], v252 offset:16128
	ds_read_b128 v[224:227], v252 offset:40704
	ds_read_b128 v[232:235], v252 offset:7936
	ds_read_b128 v[216:219], v252 offset:32512
	s_waitcnt lgkmcnt(11)
	v_pk_mul_f32 v[248:249], v[166:167], v[100:101]
	v_pk_mul_f32 v[250:251], v[166:167], v[96:97]
	v_pk_fma_f32 v[248:249], v[164:165], v[102:103], v[248:249]
	v_pk_fma_f32 v[250:251], v[164:165], v[98:99], v[250:251]
	v_add_f32_e32 v0, v248, v249
	v_pk_mul_f32 v[202:203], v[240:241], v[112:113] op_sel:[1,0]
	v_add_f32_e32 v78, v250, v251
	v_add_f32_dpp v0, v0, v0 quad_perm:[1,0,3,2] row_mask:0xf bank_mask:0xf bound_ctrl:1
	v_pk_mul_f32 v[128:129], v[240:241], v[114:115] op_sel:[1,0]
	v_add_f32_dpp v78, v78, v78 quad_perm:[1,0,3,2] row_mask:0xf bank_mask:0xf bound_ctrl:1
	v_add_f32_dpp v0, v0, v0 quad_perm:[2,3,0,1] row_mask:0xf bank_mask:0xf bound_ctrl:1
	v_pk_fma_f32 v[166:167], v[166:167], v[104:105], v[202:203]
	v_add_f32_dpp v78, v78, v78 quad_perm:[2,3,0,1] row_mask:0xf bank_mask:0xf bound_ctrl:1
	v_add_f32_dpp v0, v0, v0 row_half_mirror row_mask:0xf bank_mask:0xf bound_ctrl:1
	v_pk_fma_f32 v[164:165], v[164:165], v[106:107], v[128:129]
	v_add_f32_dpp v78, v78, v78 row_half_mirror row_mask:0xf bank_mask:0xf bound_ctrl:1
	v_add_f32_dpp v0, v0, v0 row_mirror row_mask:0xf bank_mask:0xf bound_ctrl:1
	s_nop 0
	v_add_f32_dpp v78, v78, v78 row_mirror row_mask:0xf bank_mask:0xf bound_ctrl:1
	v_pk_fma_f32 v[166:167], v[108:109], v[0:1], v[166:167] op_sel_hi:[1,0,1]
	v_pk_fma_f32 v[164:165], v[110:111], v[0:1], v[164:165] op_sel_hi:[1,0,1]
	s_waitcnt lgkmcnt(6)
; #define LAS __attribute__((address_space(3)))
; template <int CTRL> __device__ __forceinline__ float dpp_f(float x) { return __int_as_float(__builtin_amdgcn_update_dpp(0, __float_as_int(x), CTRL, 0xf, 0xf, false)); }
; __device__ __forceinline__ void phase_scan(const Params& p, LAS unsigned char* lds) {
;     ...
;                         for (int u16 = 0; u16 < 16; ++u16) {
;                             const int s = 16 * hb + u16;
;                             const int sn = (s + 1) & 31;
;                             const f32x4 a_n = *(const LAS f32x4*)(sA + sn * 64), w_n = *(const LAS f32x4*)(sW + sn * 64), b_n = *(const LAS f32x4*)(sB + sn * 64);
;                             const f32x4 k_n = *(const LAS f32x4*)(sK + sn * 64), r_n = *(const LAS f32x4*)(sR + sn * 64);
;                             const float v = vq[u16 >> 2][u16 & 3];
;                             const f32x2 vv = {v, v};
;                             f32x2 pp = S01 * (f32x2){a_[0], a_[1]}; pp = S23 * (f32x2){a_[2], a_[3]} + pp;
;                             f32x2 yy = S01 * (f32x2){rp[0], rp[1]}; yy = S23 * (f32x2){rp[2], rp[3]} + yy;
;                             float sa = pp[0] + pp[1], y = yy[0] + yy[1];
;                             sa += dpp_f<0xB1>(sa); y += dpp_f<0xB1>(y);
;                             sa += dpp_f<0x4E>(sa); y += dpp_f<0x4E>(y);
;                             sa += dpp_f<0x141>(sa); y += dpp_f<0x141>(y);
;                             sa += dpp_f<0x140>(sa); y += dpp_f<0x140>(y);
;                             sY[((s - 1) & 31) * 16 + srow] = y;
;                             const f32x2 sv = {sa, sa};
;                             S01 = S01 * (f32x2){w_[0], w_[1]} + vv * (f32x2){k_[0], k_[1]};
;                             S23 = S23 * (f32x2){w_[2], w_[3]} + vv * (f32x2){k_[2], k_[3]};
;                             S01 = sv * (f32x2){b_[0], b_[1]} + S01;
;                             S23 = sv * (f32x2){b_[2], b_[3]} + S23;
;                             rp = r_;
;                             a_ = a_n; w_ = w_n; b_ = b_n; k_ = k_n; r_ = r_n;
;                         }
; #pragma unroll
;                         for (int u = 0; u < 4; ++u) vq[u] = vn[u];
;                     }
;                     { f32x2 yy = S01 * (f32x2){rp[0], rp[1]}; yy = S23 * (f32x2){rp[2], rp[3]} + yy; sY[31 * 16 + srow] = red16(yy[0] + yy[1]); }
	v_pk_mul_f32 v[248:249], v[166:167], v[120:121]
	v_pk_mul_f32 v[250:251], v[166:167], v[116:117]
	v_pk_fma_f32 v[248:249], v[164:165], v[122:123], v[248:249]
	v_pk_fma_f32 v[250:251], v[164:165], v[118:119], v[250:251]
	v_add_f32_e32 v0, v248, v249
	v_pk_mul_f32 v[202:203], v[242:243], v[208:209] op_sel_hi:[0,1]
	v_add_f32_e32 v79, v250, v251
	v_add_f32_dpp v0, v0, v0 quad_perm:[1,0,3,2] row_mask:0xf bank_mask:0xf bound_ctrl:1
	v_pk_mul_f32 v[128:129], v[242:243], v[210:211] op_sel_hi:[0,1]
	v_add_f32_dpp v79, v79, v79 quad_perm:[1,0,3,2] row_mask:0xf bank_mask:0xf bound_ctrl:1
	v_add_f32_dpp v0, v0, v0 quad_perm:[2,3,0,1] row_mask:0xf bank_mask:0xf bound_ctrl:1
	v_pk_fma_f32 v[166:167], v[166:167], v[124:125], v[202:203]
	v_add_f32_dpp v79, v79, v79 quad_perm:[2,3,0,1] row_mask:0xf bank_mask:0xf bound_ctrl:1
	v_add_f32_dpp v0, v0, v0 row_half_mirror row_mask:0xf bank_mask:0xf bound_ctrl:1
	v_pk_fma_f32 v[164:165], v[164:165], v[126:127], v[128:129]
	v_add_f32_dpp v79, v79, v79 row_half_mirror row_mask:0xf bank_mask:0xf bound_ctrl:1
	v_add_f32_dpp v0, v0, v0 row_mirror row_mask:0xf bank_mask:0xf bound_ctrl:1
	s_nop 0
	v_add_f32_dpp v79, v79, v79 row_mirror row_mask:0xf bank_mask:0xf bound_ctrl:1
	v_pk_fma_f32 v[166:167], v[204:205], v[0:1], v[166:167] op_sel_hi:[1,0,1]
	v_pk_fma_f32 v[164:165], v[206:207], v[0:1], v[164:165] op_sel_hi:[1,0,1]
	ds_write2_b32 v255, v78, v79 offset0:192 offset1:208
	s_waitcnt lgkmcnt(1)
	v_pk_mul_f32 v[248:249], v[166:167], v[216:217]
	v_pk_mul_f32 v[250:251], v[166:167], v[212:213]
	v_pk_fma_f32 v[248:249], v[164:165], v[218:219], v[248:249]
	v_pk_fma_f32 v[250:251], v[164:165], v[214:215], v[250:251]
	v_add_f32_e32 v0, v248, v249
	v_pk_mul_f32 v[202:203], v[242:243], v[228:229] op_sel:[1,0]
	v_add_f32_e32 v78, v250, v251
	v_add_f32_dpp v0, v0, v0 quad_perm:[1,0,3,2] row_mask:0xf bank_mask:0xf bound_ctrl:1
	v_pk_mul_f32 v[128:129], v[242:243], v[230:231] op_sel:[1,0]
	v_add_f32_dpp v78, v78, v78 quad_perm:[1,0,3,2] row_mask:0xf bank_mask:0xf bound_ctrl:1
	v_add_f32_dpp v0, v0, v0 quad_perm:[2,3,0,1] row_mask:0xf bank_mask:0xf bound_ctrl:1
	v_pk_fma_f32 v[166:167], v[166:167], v[220:221], v[202:203]
	v_add_f32_dpp v78, v78, v78 quad_perm:[2,3,0,1] row_mask:0xf bank_mask:0xf bound_ctrl:1
	v_add_f32_dpp v0, v0, v0 row_half_mirror row_mask:0xf bank_mask:0xf bound_ctrl:1
	v_pk_fma_f32 v[164:165], v[164:165], v[222:223], v[128:129]
	v_add_f32_dpp v78, v78, v78 row_half_mirror row_mask:0xf bank_mask:0xf bound_ctrl:1
	v_add_f32_dpp v0, v0, v0 row_mirror row_mask:0xf bank_mask:0xf bound_ctrl:1
	s_nop 0
	v_add_f32_dpp v78, v78, v78 row_mirror row_mask:0xf bank_mask:0xf bound_ctrl:1
	v_pk_fma_f32 v[166:167], v[224:225], v[0:1], v[166:167] op_sel_hi:[1,0,1]
	v_pk_fma_f32 v[164:165], v[226:227], v[0:1], v[164:165] op_sel_hi:[1,0,1]
	v_pk_mul_f32 v[250:251], v[166:167], v[232:233]
	s_nop 0
	v_pk_fma_f32 v[250:251], v[164:165], v[234:235], v[250:251]
	s_nop 0
	v_add_f32_e32 v79, v250, v251
	s_nop 1
	v_add_f32_dpp v79, v79, v79 quad_perm:[1,0,3,2] row_mask:0xf bank_mask:0xf bound_ctrl:1
	s_nop 1
	v_add_f32_dpp v79, v79, v79 quad_perm:[2,3,0,1] row_mask:0xf bank_mask:0xf bound_ctrl:1
	s_nop 1
	v_add_f32_dpp v79, v79, v79 row_half_mirror row_mask:0xf bank_mask:0xf bound_ctrl:1
	s_nop 1
	v_add_f32_dpp v79, v79, v79 row_mirror row_mask:0xf bank_mask:0xf bound_ctrl:1
	ds_write2_b32 v255, v78, v79 offset0:224 offset1:240
	s_setprio 0
	s_branch .LBB0_603
